# QKV intermediate stored head-major [48][NTOK][64] (P1 epilogue stores + attention loads re-addressed) for contiguous attention reads
# speedup vs baseline: 1.0077x; 1.0077x over previous
.LBB0_217:
	s_lshl_b32 s37, s6, 8
	s_lshr_b32 s98, s79, 6
	s_lshl_b32 s98, s98, 21
	s_bfe_u32 s100, s79, 0x10005
	s_lshl_b32 s100, s100, 5
	s_or_b32 s98, s98, s100
	s_add_i32 s6, s72, 0xfffff400
	s_lshl_b64 s[46:47], s[6:7], 1
	s_add_u32 s6, s56, s46
	s_addc_u32 s63, s57, s47
	s_ashr_i32 s73, s72, 31
	s_lshl_b64 s[46:47], s[72:73], 16
	s_add_u32 s46, s42, s46
	s_addc_u32 s47, s43, s47
	s_cmp_lt_i32 s36, 12
	s_cselect_b32 s98, s98, s79
	s_movk_i32 s100, 0x100
	s_cselect_b32 s100, 0x800000, s100
	s_mov_b32 s101, 0
	s_cselect_b32 s6, s46, s6
	v_mov_b32_e32 v122, s6
	s_movk_i32 s6, 0x40
	v_lshl_add_u32 v120, v174, 3, s98
	s_cselect_b32 s36, s47, s63
	s_cselect_b32 s6, s6, 0x800
	s_add_i32 s37, s37, s78
	v_mov_b32_e32 v123, s36
	v_ashrrev_i32_e32 v121, 31, v120
	v_add_u32_e32 v166, s37, v173
	v_lshl_add_u64 v[120:121], v[120:121], 1, v[122:123]
	v_mad_i64_i32 v[122:123], s[36:37], s6, v166, 0
	v_lshl_add_u64 v[164:165], v[122:123], 1, v[120:121]
	v_pk_fma_f32 v[122:123], v[138:139], 0, v[142:143] op_sel_hi:[1,0,1]
	v_pk_fma_f32 v[136:137], v[136:137], 0, v[140:141] op_sel_hi:[1,0,1]
	v_pk_add_f32 v[138:139], v[118:119], v[122:123]
	v_pk_add_f32 v[140:141], v[116:117], v[136:137]
	v_pk_fma_f32 v[116:117], v[130:131], 0, v[134:135] op_sel_hi:[1,0,1]
	v_pk_fma_f32 v[118:119], v[128:129], 0, v[132:133] op_sel_hi:[1,0,1]
	v_pk_add_f32 v[114:115], v[114:115], v[116:117]
	v_pk_add_f32 v[112:113], v[112:113], v[118:119]
	s_cmp_gt_i32 s61, 1
	s_mov_b64 s[36:37], -1
	v_cvt_pk_bf16_f32 v174, v175, v177
	v_cvt_pk_bf16_f32 v175, v179, v182
	v_cvt_pk_bf16_f32 v176, v176, v178
	v_cvt_pk_bf16_f32 v177, v180, v181
	global_store_dwordx4 v[164:165], v[174:177], off
	s_cbranch_scc0 .LBB0_219
	v_mul_f32_e32 v134, 0xbfb8aa3b, v139
	v_mul_f32_e32 v128, 0xbfb8aa3b, v140
	v_mul_f32_e32 v129, 0xbfb8aa3b, v112
	v_mul_f32_e32 v130, 0xbfb8aa3b, v141
	v_mul_f32_e32 v131, 0xbfb8aa3b, v113
	v_mul_f32_e32 v132, 0xbfb8aa3b, v138
	v_mul_f32_e32 v133, 0xbfb8aa3b, v114
	v_exp_f32_e32 v134, v134
	v_mul_f32_e32 v135, 0xbfb8aa3b, v115
	v_exp_f32_e32 v128, v128
	v_exp_f32_e32 v129, v129
	v_exp_f32_e32 v130, v130
	v_exp_f32_e32 v131, v131
	v_exp_f32_e32 v132, v132
	v_exp_f32_e32 v133, v133
	v_exp_f32_e32 v142, v135
	v_add_f32_e32 v134, 1.0, v134
	v_add_f32_e32 v128, 1.0, v128
	v_add_f32_e32 v129, 1.0, v129
	v_add_f32_e32 v130, 1.0, v130
	v_add_f32_e32 v131, 1.0, v131
	v_add_f32_e32 v132, 1.0, v132
	v_add_f32_e32 v133, 1.0, v133
	v_rcp_f32_e32 v135, v134
	v_add_f32_e32 v134, 1.0, v142
	v_rcp_f32_e32 v128, v128
	v_rcp_f32_e32 v129, v129
	v_rcp_f32_e32 v130, v130
	v_rcp_f32_e32 v131, v131
	v_rcp_f32_e32 v132, v132
	v_rcp_f32_e32 v133, v133
	v_rcp_f32_e32 v134, v134
	s_mov_b64 s[36:37], 0

.LBB0_223:
	v_cvt_pk_bf16_f32 v112, v128, v130
	v_cvt_pk_bf16_f32 v113, v132, v135
	v_cvt_pk_bf16_f32 v114, v129, v131
	v_cvt_pk_bf16_f32 v115, v133, v134
	v_pk_add_f32 v[110:111], v[110:111], v[160:161]
	v_pk_add_f32 v[108:109], v[108:109], v[162:163]
	v_pk_add_f32 v[106:107], v[106:107], v[124:125]
	v_pk_add_f32 v[104:105], v[104:105], v[126:127]
	s_cmp_gt_i32 s61, 1
	s_mov_b64 s[36:37], -1
	v_lshl_add_u64 v[210:211], v[164:165], 0, s[100:101]
	global_store_dwordx4 v[210:211], v[112:115], off
	s_cbranch_scc0 .LBB0_225
	v_mul_f32_e32 v130, 0xbfb8aa3b, v111
	v_mul_f32_e32 v112, 0xbfb8aa3b, v108
	v_mul_f32_e32 v113, 0xbfb8aa3b, v104
	v_mul_f32_e32 v114, 0xbfb8aa3b, v109
	v_mul_f32_e32 v115, 0xbfb8aa3b, v105
	v_mul_f32_e32 v128, 0xbfb8aa3b, v110
	v_mul_f32_e32 v129, 0xbfb8aa3b, v106
	v_exp_f32_e32 v130, v130
	v_mul_f32_e32 v131, 0xbfb8aa3b, v107
	v_exp_f32_e32 v112, v112
	v_exp_f32_e32 v113, v113
	v_exp_f32_e32 v114, v114
	v_exp_f32_e32 v115, v115
	v_exp_f32_e32 v128, v128
	v_exp_f32_e32 v129, v129
	v_exp_f32_e32 v132, v131
	v_add_f32_e32 v130, 1.0, v130
	v_add_f32_e32 v112, 1.0, v112
	v_add_f32_e32 v113, 1.0, v113
	v_add_f32_e32 v114, 1.0, v114
	v_add_f32_e32 v115, 1.0, v115
	v_add_f32_e32 v128, 1.0, v128
	v_add_f32_e32 v129, 1.0, v129
	v_rcp_f32_e32 v131, v130
	v_add_f32_e32 v130, 1.0, v132
	v_rcp_f32_e32 v112, v112
	v_rcp_f32_e32 v113, v113
	v_rcp_f32_e32 v114, v114
	v_rcp_f32_e32 v115, v115
	v_rcp_f32_e32 v128, v128
	v_rcp_f32_e32 v129, v129
	v_rcp_f32_e32 v130, v130
	s_mov_b64 s[36:37], 0

.LBB0_235:
	v_cvt_pk_bf16_f32 v96, v106, v108
	v_cvt_pk_bf16_f32 v97, v110, v113
	v_cvt_pk_bf16_f32 v98, v107, v109
	v_cvt_pk_bf16_f32 v99, v111, v112
	v_pk_add_f32 v[94:95], v[94:95], v[160:161]
	v_pk_add_f32 v[92:93], v[92:93], v[162:163]
	v_pk_add_f32 v[90:91], v[90:91], v[124:125]
	v_pk_add_f32 v[88:89], v[88:89], v[126:127]
	s_cmp_gt_i32 s61, 1
	s_mov_b64 s[36:37], -1
	v_lshl_add_u64 v[210:211], v[104:105], 0, s[100:101]
	global_store_dwordx4 v[210:211], v[96:99], off
	s_cbranch_scc0 .LBB0_237
	v_mul_f32_e32 v102, 0xbfb8aa3b, v95
	v_mul_f32_e32 v96, 0xbfb8aa3b, v92
	v_mul_f32_e32 v97, 0xbfb8aa3b, v88
	v_mul_f32_e32 v98, 0xbfb8aa3b, v93
	v_mul_f32_e32 v99, 0xbfb8aa3b, v89
	v_mul_f32_e32 v100, 0xbfb8aa3b, v94
	v_mul_f32_e32 v101, 0xbfb8aa3b, v90
	v_exp_f32_e32 v102, v102
	v_mul_f32_e32 v103, 0xbfb8aa3b, v91
	v_exp_f32_e32 v96, v96
	v_exp_f32_e32 v97, v97
	v_exp_f32_e32 v98, v98
	v_exp_f32_e32 v99, v99
	v_exp_f32_e32 v100, v100
	v_exp_f32_e32 v101, v101
	v_exp_f32_e32 v104, v103
	v_add_f32_e32 v102, 1.0, v102
	v_add_f32_e32 v96, 1.0, v96
	v_add_f32_e32 v97, 1.0, v97
	v_add_f32_e32 v98, 1.0, v98
	v_add_f32_e32 v99, 1.0, v99
	v_add_f32_e32 v100, 1.0, v100
	v_add_f32_e32 v101, 1.0, v101
	v_rcp_f32_e32 v103, v102
	v_add_f32_e32 v102, 1.0, v104
	v_rcp_f32_e32 v96, v96
	v_rcp_f32_e32 v97, v97
	v_rcp_f32_e32 v98, v98
	v_rcp_f32_e32 v99, v99
	v_rcp_f32_e32 v100, v100
	v_rcp_f32_e32 v101, v101
	v_rcp_f32_e32 v102, v102
	s_mov_b64 s[36:37], 0

.LBB0_247:
	v_cvt_pk_bf16_f32 v80, v90, v92
	v_cvt_pk_bf16_f32 v81, v94, v97
	v_cvt_pk_bf16_f32 v82, v91, v93
	v_cvt_pk_bf16_f32 v83, v95, v96
	v_pk_add_f32 v[78:79], v[78:79], v[160:161]
	v_pk_add_f32 v[76:77], v[76:77], v[162:163]
	v_pk_add_f32 v[74:75], v[74:75], v[124:125]
	v_pk_add_f32 v[72:73], v[72:73], v[126:127]
	s_cmp_gt_i32 s61, 1
	s_mov_b64 s[36:37], -1
	v_lshl_add_u64 v[210:211], v[88:89], 0, s[100:101]
	global_store_dwordx4 v[210:211], v[80:83], off
	s_cbranch_scc0 .LBB0_249
	v_mul_f32_e32 v86, 0xbfb8aa3b, v79
	v_mul_f32_e32 v80, 0xbfb8aa3b, v76
	v_mul_f32_e32 v81, 0xbfb8aa3b, v72
	v_mul_f32_e32 v82, 0xbfb8aa3b, v77
	v_mul_f32_e32 v83, 0xbfb8aa3b, v73
	v_mul_f32_e32 v84, 0xbfb8aa3b, v78
	v_mul_f32_e32 v85, 0xbfb8aa3b, v74
	v_exp_f32_e32 v86, v86
	v_mul_f32_e32 v87, 0xbfb8aa3b, v75
	v_exp_f32_e32 v80, v80
	v_exp_f32_e32 v81, v81
	v_exp_f32_e32 v82, v82
	v_exp_f32_e32 v83, v83
	v_exp_f32_e32 v84, v84
	v_exp_f32_e32 v85, v85
	v_exp_f32_e32 v88, v87
	v_add_f32_e32 v86, 1.0, v86
	v_add_f32_e32 v80, 1.0, v80
	v_add_f32_e32 v81, 1.0, v81
	v_add_f32_e32 v82, 1.0, v82
	v_add_f32_e32 v83, 1.0, v83
	v_add_f32_e32 v84, 1.0, v84
	v_add_f32_e32 v85, 1.0, v85
	v_rcp_f32_e32 v87, v86
	v_add_f32_e32 v86, 1.0, v88
	v_rcp_f32_e32 v80, v80
	v_rcp_f32_e32 v81, v81
	v_rcp_f32_e32 v82, v82
	v_rcp_f32_e32 v83, v83
	v_rcp_f32_e32 v84, v84
	v_rcp_f32_e32 v85, v85
	v_rcp_f32_e32 v86, v86
	s_mov_b64 s[36:37], 0

.LBB0_259:
	v_cvt_pk_bf16_f32 v64, v74, v76
	v_cvt_pk_bf16_f32 v65, v78, v81
	v_cvt_pk_bf16_f32 v66, v75, v77
	v_cvt_pk_bf16_f32 v67, v79, v80
	v_pk_add_f32 v[62:63], v[62:63], v[160:161]
	v_pk_add_f32 v[60:61], v[60:61], v[162:163]
	v_pk_add_f32 v[58:59], v[58:59], v[124:125]
	v_pk_add_f32 v[56:57], v[56:57], v[126:127]
	s_cmp_gt_i32 s61, 1
	s_mov_b64 s[36:37], -1
	v_lshl_add_u64 v[210:211], v[72:73], 0, s[100:101]
	global_store_dwordx4 v[210:211], v[64:67], off
	s_cbranch_scc0 .LBB0_261
	v_mul_f32_e32 v70, 0xbfb8aa3b, v63
	v_mul_f32_e32 v64, 0xbfb8aa3b, v60
	v_mul_f32_e32 v65, 0xbfb8aa3b, v56
	v_mul_f32_e32 v66, 0xbfb8aa3b, v61
	v_mul_f32_e32 v67, 0xbfb8aa3b, v57
	v_mul_f32_e32 v68, 0xbfb8aa3b, v62
	v_mul_f32_e32 v69, 0xbfb8aa3b, v58
	v_exp_f32_e32 v70, v70
	v_mul_f32_e32 v71, 0xbfb8aa3b, v59
	v_exp_f32_e32 v64, v64
	v_exp_f32_e32 v65, v65
	v_exp_f32_e32 v66, v66
	v_exp_f32_e32 v67, v67
	v_exp_f32_e32 v68, v68
	v_exp_f32_e32 v69, v69
	v_exp_f32_e32 v72, v71
	v_add_f32_e32 v70, 1.0, v70
	v_add_f32_e32 v64, 1.0, v64
	v_add_f32_e32 v65, 1.0, v65
	v_add_f32_e32 v66, 1.0, v66
	v_add_f32_e32 v67, 1.0, v67
	v_add_f32_e32 v68, 1.0, v68
	v_add_f32_e32 v69, 1.0, v69
	v_rcp_f32_e32 v71, v70
	v_add_f32_e32 v70, 1.0, v72
	v_rcp_f32_e32 v64, v64
	v_rcp_f32_e32 v65, v65
	v_rcp_f32_e32 v66, v66
	v_rcp_f32_e32 v67, v67
	v_rcp_f32_e32 v68, v68
	v_rcp_f32_e32 v69, v69
	v_rcp_f32_e32 v70, v70
	s_mov_b64 s[36:37], 0

.LBB0_271:
	v_cvt_pk_bf16_f32 v48, v58, v60
	v_cvt_pk_bf16_f32 v49, v62, v65
	v_cvt_pk_bf16_f32 v50, v59, v61
	v_cvt_pk_bf16_f32 v51, v63, v64
	v_pk_add_f32 v[46:47], v[46:47], v[160:161]
	v_pk_add_f32 v[44:45], v[44:45], v[162:163]
	v_pk_add_f32 v[42:43], v[42:43], v[124:125]
	v_pk_add_f32 v[40:41], v[40:41], v[126:127]
	s_cmp_gt_i32 s61, 1
	s_mov_b64 s[36:37], -1
	v_lshl_add_u64 v[210:211], v[56:57], 0, s[100:101]
	global_store_dwordx4 v[210:211], v[48:51], off
	s_cbranch_scc0 .LBB0_273
	v_mul_f32_e32 v54, 0xbfb8aa3b, v47
	v_mul_f32_e32 v48, 0xbfb8aa3b, v44
	v_mul_f32_e32 v49, 0xbfb8aa3b, v40
	v_mul_f32_e32 v50, 0xbfb8aa3b, v45
	v_mul_f32_e32 v51, 0xbfb8aa3b, v41
	v_mul_f32_e32 v52, 0xbfb8aa3b, v46
	v_mul_f32_e32 v53, 0xbfb8aa3b, v42
	v_exp_f32_e32 v54, v54
	v_mul_f32_e32 v55, 0xbfb8aa3b, v43
	v_exp_f32_e32 v48, v48
	v_exp_f32_e32 v49, v49
	v_exp_f32_e32 v50, v50
	v_exp_f32_e32 v51, v51
	v_exp_f32_e32 v52, v52
	v_exp_f32_e32 v53, v53
	v_exp_f32_e32 v56, v55
	v_add_f32_e32 v54, 1.0, v54
	v_add_f32_e32 v48, 1.0, v48
	v_add_f32_e32 v49, 1.0, v49
	v_add_f32_e32 v50, 1.0, v50
	v_add_f32_e32 v51, 1.0, v51
	v_add_f32_e32 v52, 1.0, v52
	v_add_f32_e32 v53, 1.0, v53
	v_rcp_f32_e32 v55, v54
	v_add_f32_e32 v54, 1.0, v56
	v_rcp_f32_e32 v48, v48
	v_rcp_f32_e32 v49, v49
	v_rcp_f32_e32 v50, v50
	v_rcp_f32_e32 v51, v51
	v_rcp_f32_e32 v52, v52
	v_rcp_f32_e32 v53, v53
	v_rcp_f32_e32 v54, v54
	s_mov_b64 s[36:37], 0

.LBB0_283:
	v_cvt_pk_bf16_f32 v32, v42, v44
	v_cvt_pk_bf16_f32 v33, v46, v49
	v_cvt_pk_bf16_f32 v34, v43, v45
	v_cvt_pk_bf16_f32 v35, v47, v48
	v_pk_add_f32 v[30:31], v[30:31], v[160:161]
	v_pk_add_f32 v[28:29], v[28:29], v[162:163]
	v_pk_add_f32 v[26:27], v[26:27], v[124:125]
	v_pk_add_f32 v[24:25], v[24:25], v[126:127]
	s_cmp_gt_i32 s61, 1
	s_mov_b64 s[36:37], -1
	v_lshl_add_u64 v[210:211], v[40:41], 0, s[100:101]
	global_store_dwordx4 v[210:211], v[32:35], off
	s_cbranch_scc0 .LBB0_285
	v_mul_f32_e32 v38, 0xbfb8aa3b, v31
	v_mul_f32_e32 v32, 0xbfb8aa3b, v28
	v_mul_f32_e32 v33, 0xbfb8aa3b, v24
	v_mul_f32_e32 v34, 0xbfb8aa3b, v29
	v_mul_f32_e32 v35, 0xbfb8aa3b, v25
	v_mul_f32_e32 v36, 0xbfb8aa3b, v30
	v_mul_f32_e32 v37, 0xbfb8aa3b, v26
	v_exp_f32_e32 v38, v38
	v_mul_f32_e32 v39, 0xbfb8aa3b, v27
	v_exp_f32_e32 v32, v32
	v_exp_f32_e32 v33, v33
	v_exp_f32_e32 v34, v34
	v_exp_f32_e32 v35, v35
	v_exp_f32_e32 v36, v36
	v_exp_f32_e32 v37, v37
	v_exp_f32_e32 v40, v39
	v_add_f32_e32 v38, 1.0, v38
	v_add_f32_e32 v32, 1.0, v32
	v_add_f32_e32 v33, 1.0, v33
	v_add_f32_e32 v34, 1.0, v34
	v_add_f32_e32 v35, 1.0, v35
	v_add_f32_e32 v36, 1.0, v36
	v_add_f32_e32 v37, 1.0, v37
	v_rcp_f32_e32 v39, v38
	v_add_f32_e32 v38, 1.0, v40
	v_rcp_f32_e32 v32, v32
	v_rcp_f32_e32 v33, v33
	v_rcp_f32_e32 v34, v34
	v_rcp_f32_e32 v35, v35
	v_rcp_f32_e32 v36, v36
	v_rcp_f32_e32 v37, v37
	v_rcp_f32_e32 v38, v38
	s_mov_b64 s[36:37], 0

.LBB0_295:
	v_cvt_pk_bf16_f32 v16, v26, v28
	v_cvt_pk_bf16_f32 v17, v30, v33
	v_cvt_pk_bf16_f32 v18, v27, v29
	v_cvt_pk_bf16_f32 v19, v31, v32
	v_pk_add_f32 v[14:15], v[14:15], v[160:161]
	v_pk_add_f32 v[12:13], v[12:13], v[162:163]
	v_pk_add_f32 v[10:11], v[10:11], v[124:125]
	v_pk_add_f32 v[8:9], v[8:9], v[126:127]
	s_cmp_gt_i32 s61, 1
	s_mov_b64 s[36:37], -1
	v_lshl_add_u64 v[210:211], v[24:25], 0, s[100:101]
	global_store_dwordx4 v[210:211], v[16:19], off
	s_cbranch_scc0 .LBB0_297
	v_mul_f32_e32 v22, 0xbfb8aa3b, v15
	v_mul_f32_e32 v16, 0xbfb8aa3b, v12
	v_mul_f32_e32 v17, 0xbfb8aa3b, v8
	v_mul_f32_e32 v18, 0xbfb8aa3b, v13
	v_mul_f32_e32 v19, 0xbfb8aa3b, v9
	v_mul_f32_e32 v20, 0xbfb8aa3b, v14
	v_mul_f32_e32 v21, 0xbfb8aa3b, v10
	v_exp_f32_e32 v22, v22
	v_mul_f32_e32 v23, 0xbfb8aa3b, v11
	v_exp_f32_e32 v16, v16
	v_exp_f32_e32 v17, v17
	v_exp_f32_e32 v18, v18
	v_exp_f32_e32 v19, v19
	v_exp_f32_e32 v20, v20
	v_exp_f32_e32 v21, v21
	v_exp_f32_e32 v24, v23
	v_add_f32_e32 v22, 1.0, v22
	v_add_f32_e32 v16, 1.0, v16
	v_add_f32_e32 v17, 1.0, v17
	v_add_f32_e32 v18, 1.0, v18
	v_add_f32_e32 v19, 1.0, v19
	v_add_f32_e32 v20, 1.0, v20
	v_add_f32_e32 v21, 1.0, v21
	v_rcp_f32_e32 v23, v22
	v_add_f32_e32 v22, 1.0, v24
	v_rcp_f32_e32 v16, v16
	v_rcp_f32_e32 v17, v17
	v_rcp_f32_e32 v18, v18
	v_rcp_f32_e32 v19, v19
	v_rcp_f32_e32 v20, v20
	v_rcp_f32_e32 v21, v21
	v_rcp_f32_e32 v22, v22
	s_mov_b64 s[36:37], 0

.LBB0_307:
	s_andn2_b64 vcc, exec, s[4:5]
	s_mov_b64 s[4:5], -1
	v_cvt_pk_bf16_f32 v0, v10, v12
	v_cvt_pk_bf16_f32 v1, v14, v17
	v_cvt_pk_bf16_f32 v2, v11, v13
	v_cvt_pk_bf16_f32 v3, v15, v16
	v_lshl_add_u64 v[210:211], v[8:9], 0, s[100:101]
	global_store_dwordx4 v[210:211], v[0:3], off
	s_mov_b32 s99, 1
	s_cbranch_vccnz .LBB0_202
	s_andn2_b64 vcc, exec, s[8:9]
	s_cbranch_vccnz .LBB0_201
	s_barrier
	s_branch .LBB0_201

.LBB0_368:
	v_readlane_b32 s14, v255, 16
	v_bfe_u32 v7, v6, 5, 1
	v_readlane_b32 s15, v255, 17
	v_and_b32_e32 v139, 31, v6
	s_and_b64 vcc, exec, s[14:15]
	v_lshlrev_b32_e32 v132, 4, v7
	v_lshlrev_b32_e32 v8, 4, v6
	v_ashrrev_i32_e32 v176, 3, v6
	s_cbranch_vccnz .LBB0_382
	s_ashr_i32 s7, s6, 31
	s_lshl_b64 s[14:15], s[6:7], 14
	s_or_b32 s14, s14, s67
	v_add_u32_e32 v2, s13, v139
	v_mov_b64_e32 v[0:1], s[14:15]
	v_mad_i64_i32 v[0:1], s[36:37], v2, s1, v[0:1]
	s_movk_i32 s7, 0x80
	v_mov_b64_e32 v[2:3], s[42:43]
	v_mad_u64_u32 v[2:3], s[36:37], v0, s7, v[2:3]
	v_mov_b32_e32 v0, v3
	v_mad_u64_u32 v[0:1], s[36:37], v1, s7, v[0:1]
	v_mov_b32_e32 v3, v0
	s_ashr_i32 s5, s4, 31
	v_mov_b32_e32 v64, 0
	s_lshl_b64 s[100:101], s[4:5], 15
	v_lshl_add_u64 v[0:1], s[100:101], 1, v[2:3]
	v_mov_b32_e32 v133, v64
	v_lshl_add_u64 v[0:1], v[0:1], 0, v[132:133]
	global_load_dwordx4 v[48:51], v[0:1], off
	global_load_dwordx4 v[52:55], v[0:1], off offset:32
	global_load_dwordx4 v[56:59], v[0:1], off offset:64
	global_load_dwordx4 v[60:63], v[0:1], off offset:96
	v_and_b32_e32 v0, 0x70, v8
	v_mov_b32_e32 v1, v64
	v_lshl_add_u64 v[4:5], s[42:43], 0, v[0:1]
	v_add_u32_e32 v0, s97, v176
	v_add_u32_e32 v0, 0xffffff80, v0
	v_mov_b32_e32 v76, 0
	v_mov_b32_e32 v77, v64
	v_cmp_gt_i32_e32 vcc, s66, v176
	v_cmp_lt_i32_e64 s[4:5], -1, v0
	v_mov_b32_e32 v78, v64
	v_mov_b32_e32 v79, v64
	v_mov_b64_e32 v[72:73], v[76:77]
	s_and_b64 s[36:37], vcc, s[4:5]
	s_mov_b32 s9, 0
	v_mov_b64_e32 v[74:75], v[78:79]
	v_mov_b32_e32 v68, 0
	v_mov_b32_e32 v69, 0
	v_mov_b32_e32 v70, 0
	v_mov_b32_e32 v71, 0
	s_and_saveexec_b64 s[4:5], s[36:37]
	s_cbranch_execz .LBB0_371
	v_mov_b64_e32 v[2:3], s[14:15]
	v_mad_u64_u32 v[0:1], s[36:37], v0, s1, v[2:3]
	v_mad_u64_u32 v[2:3], s[36:37], v0, s7, v[4:5]
	v_mov_b32_e32 v0, v3
	v_mad_u64_u32 v[0:1], s[36:37], v1, s7, v[0:1]
	v_mov_b32_e32 v3, v0
	s_lshl_b64 s[100:101], s[8:9], 15
	v_lshl_add_u64 v[0:1], s[100:101], 1, v[2:3]
	s_mov_b32 s11, s9
	s_lshl_b64 s[100:101], s[10:11], 15
	v_lshl_add_u64 v[2:3], s[100:101], 1, v[2:3]
	global_load_dwordx4 v[68:71], v[0:1], off
	global_load_dwordx4 v[72:75], v[2:3], off
.LBB0_371:
	s_or_b64 exec, exec, s[4:5]
	v_add_u32_e32 v0, 0x200, v6
	v_ashrrev_i32_e32 v1, 3, v0
	v_add_u32_e32 v0, s97, v1
	v_add_u32_e32 v0, 0xffffff80, v0
	v_cmp_gt_i32_e32 vcc, s66, v1
	v_cmp_lt_i32_e64 s[4:5], -1, v0
	s_and_b64 s[36:37], vcc, s[4:5]
	v_mov_b32_e32 v65, 0
	v_mov_b32_e32 v66, 0
	v_mov_b32_e32 v67, 0
	s_and_saveexec_b64 s[4:5], s[36:37]
	s_cbranch_execz .LBB0_373
	v_mov_b64_e32 v[2:3], s[14:15]
	v_mad_u64_u32 v[0:1], s[36:37], v0, s1, v[2:3]
	v_mad_u64_u32 v[2:3], s[36:37], v0, s7, v[4:5]
	v_mov_b32_e32 v0, v3
	v_mad_u64_u32 v[0:1], s[36:37], v1, s7, v[0:1]
	v_mov_b32_e32 v3, v0
	s_lshl_b64 s[100:101], s[8:9], 15
	v_lshl_add_u64 v[0:1], s[100:101], 1, v[2:3]
	s_mov_b32 s11, s9
	s_lshl_b64 s[100:101], s[10:11], 15
	v_lshl_add_u64 v[2:3], s[100:101], 1, v[2:3]
	global_load_dwordx4 v[64:67], v[0:1], off
	global_load_dwordx4 v[76:79], v[2:3], off
.LBB0_373:
	s_or_b64 exec, exec, s[4:5]
	v_add_u32_e32 v0, 0x400, v6
	v_ashrrev_i32_e32 v1, 3, v0
	v_add_u32_e32 v0, s97, v1
	v_mov_b32_e32 v96, 0
	v_add_u32_e32 v0, 0xffffff80, v0
	v_mov_b32_e32 v97, v96
	v_cmp_gt_i32_e32 vcc, s66, v1
	v_cmp_lt_i32_e64 s[4:5], -1, v0
	v_mov_b32_e32 v98, v96
	v_mov_b32_e32 v99, v96
	v_mov_b64_e32 v[84:85], v[96:97]
	s_and_b64 s[36:37], vcc, s[4:5]
	v_mov_b64_e32 v[86:87], v[98:99]
	v_mov_b32_e32 v80, v96
	v_mov_b32_e32 v81, v96
	v_mov_b32_e32 v82, v96
	v_mov_b32_e32 v83, v96
	s_and_saveexec_b64 s[4:5], s[36:37]
	s_cbranch_execz .LBB0_375
	v_mov_b64_e32 v[2:3], s[14:15]
	v_mad_u64_u32 v[0:1], s[36:37], v0, s1, v[2:3]
	v_mad_u64_u32 v[2:3], s[36:37], v0, s7, v[4:5]
	v_mov_b32_e32 v0, v3
	v_mad_u64_u32 v[0:1], s[36:37], v1, s7, v[0:1]
	v_mov_b32_e32 v3, v0
	s_lshl_b64 s[100:101], s[8:9], 15
	v_lshl_add_u64 v[0:1], s[100:101], 1, v[2:3]
	s_mov_b32 s11, s9
	s_lshl_b64 s[100:101], s[10:11], 15
	v_lshl_add_u64 v[2:3], s[100:101], 1, v[2:3]
	global_load_dwordx4 v[80:83], v[0:1], off
	global_load_dwordx4 v[84:87], v[2:3], off
.LBB0_375:
	s_or_b64 exec, exec, s[4:5]
	v_add_u32_e32 v0, 0x600, v6
	v_ashrrev_i32_e32 v1, 3, v0
	v_add_u32_e32 v0, s97, v1
	v_add_u32_e32 v0, 0xffffff80, v0
	v_cmp_gt_i32_e32 vcc, s66, v1
	v_cmp_lt_i32_e64 s[4:5], -1, v0
	s_and_b64 s[36:37], vcc, s[4:5]
	v_mov_b32_e32 v92, v96
	v_mov_b32_e32 v93, v96
	v_mov_b32_e32 v94, v96
	v_mov_b32_e32 v95, v96
	s_and_saveexec_b64 s[4:5], s[36:37]
	s_cbranch_execz .LBB0_377
	v_mov_b64_e32 v[2:3], s[14:15]
	v_mad_u64_u32 v[0:1], s[36:37], v0, s1, v[2:3]
	v_mad_u64_u32 v[2:3], s[36:37], v0, s7, v[4:5]
	v_mov_b32_e32 v0, v3
	v_mad_u64_u32 v[0:1], s[36:37], v1, s7, v[0:1]
	v_mov_b32_e32 v3, v0
	s_lshl_b64 s[100:101], s[8:9], 15
	v_lshl_add_u64 v[0:1], s[100:101], 1, v[2:3]
	s_mov_b32 s11, s9
	s_lshl_b64 s[100:101], s[10:11], 15
	v_lshl_add_u64 v[2:3], s[100:101], 1, v[2:3]
	global_load_dwordx4 v[92:95], v[0:1], off
	global_load_dwordx4 v[96:99], v[2:3], off
.LBB0_377:
	s_or_b64 exec, exec, s[4:5]
	v_add_u32_e32 v0, 0x800, v6
	v_ashrrev_i32_e32 v0, 3, v0
	v_add_u32_e32 v1, s97, v0
	v_cmp_gt_i32_e32 vcc, s66, v0
	v_mov_b32_e32 v0, 0
	v_add_u32_e32 v9, 0xffffff80, v1
	v_mov_b32_e32 v2, v0
	v_mov_b32_e32 v3, v0
	v_cmp_lt_i32_e64 s[4:5], -1, v9
	v_mov_b32_e32 v1, v0
	v_mov_b64_e32 v[106:107], v[2:3]
	s_and_b64 s[36:37], vcc, s[4:5]
	v_mov_b64_e32 v[104:105], v[0:1]
	v_mov_b32_e32 v100, 0
	v_mov_b32_e32 v101, 0
	v_mov_b32_e32 v102, 0
	v_mov_b32_e32 v103, 0
	s_and_saveexec_b64 s[4:5], s[36:37]
	s_cbranch_execz .LBB0_379
	v_mov_b64_e32 v[2:3], s[14:15]
	v_mad_u64_u32 v[2:3], s[36:37], v9, s1, v[2:3]
	v_mad_u64_u32 v[10:11], s[36:37], v2, s7, v[4:5]
	v_mov_b32_e32 v2, v11
	v_mad_u64_u32 v[2:3], s[36:37], v3, s7, v[2:3]
	v_mov_b32_e32 v11, v2
	s_lshl_b64 s[100:101], s[8:9], 15
	v_lshl_add_u64 v[2:3], s[100:101], 1, v[10:11]
	s_mov_b32 s11, s9
	s_lshl_b64 s[100:101], s[10:11], 15
	v_lshl_add_u64 v[10:11], s[100:101], 1, v[10:11]
	global_load_dwordx4 v[100:103], v[2:3], off
	global_load_dwordx4 v[104:107], v[10:11], off
.LBB0_379:
	s_or_b64 exec, exec, s[4:5]
	v_add_u32_e32 v1, 0xa00, v6
	v_ashrrev_i32_e32 v2, 3, v1
	v_add_u32_e32 v1, s97, v2
	v_add_u32_e32 v1, 0xffffff80, v1
	v_cmp_gt_i32_e32 vcc, s66, v2
	v_cmp_lt_i32_e64 s[4:5], -1, v1
	s_and_b64 s[36:37], vcc, s[4:5]
	v_mov_b32_e32 v110, 0
	v_mov_b32_e32 v109, 0
	v_mov_b32_e32 v108, 0
	v_mov_b32_e32 v115, 0
	v_mov_b32_e32 v114, 0
	v_mov_b32_e32 v113, 0
	v_mov_b32_e32 v112, 0
	s_and_saveexec_b64 s[4:5], s[36:37]
	s_cbranch_execz .LBB0_381
	v_mov_b64_e32 v[2:3], s[14:15]
	v_mad_u64_u32 v[0:1], s[14:15], v1, s1, v[2:3]
	v_mad_u64_u32 v[2:3], s[14:15], v0, s7, v[4:5]
	v_mov_b32_e32 v0, v3
	v_mad_u64_u32 v[0:1], s[14:15], v1, s7, v[0:1]
	v_mov_b32_e32 v3, v0
	s_lshl_b64 s[100:101], s[8:9], 15
	v_lshl_add_u64 v[0:1], s[100:101], 1, v[2:3]
	s_mov_b32 s11, s9
	s_lshl_b64 s[100:101], s[10:11], 15
	v_lshl_add_u64 v[2:3], s[100:101], 1, v[2:3]
	global_load_dwordx4 v[108:111], v[0:1], off
	global_load_dwordx4 v[112:115], v[2:3], off
	s_waitcnt vmcnt(1)
	v_mov_b32_e32 v0, v111

.LBB0_383:
	s_add_u32 s4, s58, 0x100000
	s_addc_u32 s5, s59, 0
	v_writelane_b32 v255, s4, 22
	v_and_b32_e32 v0, 63, v6
	s_nop 0
	v_writelane_b32 v255, s5, 23
	s_nop 0
	v_readlane_b32 s4, v255, 16
	v_readlane_b32 s5, v255, 17
	s_and_b64 vcc, exec, s[4:5]
	s_cbranch_vccnz .LBB0_429
	v_mov_b32_e32 v88, 0
	v_and_b32_e32 v2, 0x70, v8
	v_mov_b32_e32 v3, v88
	v_add_u32_e32 v1, 0, v2
	v_lshl_add_u64 v[136:137], s[42:43], 0, v[2:3]
	v_add_u32_e32 v2, 0x200, v6
	v_ashrrev_i32_e32 v177, 3, v2
	v_add_u32_e32 v2, 0x400, v6
	v_ashrrev_i32_e32 v179, 3, v2
	v_add_u32_e32 v2, 0x600, v6
	s_ashr_i32 s4, s35, 7
	v_ashrrev_i32_e32 v181, 3, v2
	v_add_u32_e32 v2, 0x800, v6
	v_writelane_b32 v255, s4, 24
	v_ashrrev_i32_e32 v183, 3, v2
	v_add_u32_e32 v2, 0xa00, v6
	v_cmp_gt_u32_e64 s[4:5], 32, v0
	v_and_b32_e32 v0, 3, v6
	v_ashrrev_i32_e32 v185, 3, v2
	v_lshlrev_b32_e32 v4, 1, v6
	v_lshrrev_b32_e32 v2, 1, v6
	s_movk_i32 s83, 0x90
	v_lshlrev_b32_e32 v0, 3, v0
	s_lshl_b32 s81, s34, 5
	v_lshlrev_b32_e32 v134, 3, v7
	v_and_b32_e32 v3, 19, v6
	v_and_b32_e32 v5, 8, v4
	v_and_b32_e32 v8, 4, v2
	v_lshrrev_b32_e32 v9, 2, v6
	v_lshlrev_b32_e32 v2, 2, v7
	v_mul_lo_u32 v7, v176, s83
	v_mul_lo_u32 v10, v177, s83
	v_mul_lo_u32 v11, v179, s83
	v_mul_lo_u32 v12, v181, s83
	v_mul_lo_u32 v13, v183, s83
	v_mul_lo_u32 v14, v185, s83
	v_and_or_b32 v138, v4, 32, v0
	s_mov_b32 s34, 0x41a00000
	s_mov_b32 s36, 2.0
	s_mov_b32 s60, 4.0
	s_mov_b32 s62, 0x40c00000
	s_mov_b32 s64, 0x41800000
	s_mov_b32 s70, 0x41900000
	s_mov_b32 s72, 0x41b00000
	v_mbcnt_lo_u32_b32 v0, -1, 0
	s_mov_b32 s15, 0
	s_and_b32 s82, s81, 32
	v_add_u32_e32 v133, 0xffffff80, v176
	v_add_u32_e32 v178, 0xffffff80, v177
	v_add_u32_e32 v180, 0xffffff80, v179
	v_add_u32_e32 v182, 0xffffff80, v181
	v_add_u32_e32 v184, 0xffffff80, v183
	v_add_u32_e32 v186, 0xffffff80, v185
	v_cndmask_b32_e64 v187, 0, 1.0, s[4:5]
	v_sub_u32_e32 v188, v139, v134
	v_and_or_b32 v189, v9, 3, v134
	v_or3_b32 v190, v3, v5, v8
	v_add_u32_e32 v191, v1, v7
	v_add_u32_e32 v192, v1, v10
	v_add_u32_e32 v193, v1, v11
	v_add_u32_e32 v194, v1, v12
	v_add_u32_e32 v195, v1, v13
	v_add_u32_e32 v196, v1, v14
	s_movk_i32 s84, 0x80
	s_mov_b32 s35, 0x41a80000
	s_mov_b32 s37, 0x40400000
	s_mov_b32 s61, 0x40a00000
	s_mov_b32 s63, 0x40e00000
	s_mov_b32 s65, 0x41880000
	s_mov_b32 s71, 0x41980000
	s_mov_b32 s73, 0x41b80000
	s_mov_b32 s85, 0xff800000
	v_lshlrev_b32_e32 v140, 1, v2
	v_mov_b32_e32 v197, 0x3fb8aa3b
	v_mov_b32_e32 v198, 0x42800000
	v_mbcnt_hi_u32_b32 v199, -1, v0
	v_mov_b32_e32 v200, 0xff800000
	s_mov_b32 s86, s2
	s_waitcnt vmcnt(0)
	s_branch .LBB0_386

.LBB0_404:
	s_ashr_i32 s77, s76, 31
	s_lshl_b64 s[46:47], s[76:77], 14
	s_or_b32 s46, s46, s91
	v_add_u32_e32 v2, s88, v139
	v_mov_b64_e32 v[0:1], s[46:47]
	v_mad_i64_i32 v[0:1], vcc, v2, s90, v[0:1]
	v_mov_b64_e32 v[2:3], s[42:43]
	v_mad_u64_u32 v[2:3], vcc, v0, s84, v[2:3]
	v_mov_b32_e32 v0, v3
	v_mad_u64_u32 v[0:1], vcc, v1, s84, v[0:1]
	v_mov_b32_e32 v3, v0
	s_ashr_i32 s9, s8, 31
	s_lshl_b64 s[100:101], s[8:9], 15
	v_lshl_add_u64 v[0:1], s[100:101], 1, v[2:3]
	v_lshlrev_b32_e32 v2, 1, v134
	v_mov_b32_e32 v3, v88
	v_lshl_add_u64 v[0:1], v[0:1], 0, v[2:3]
	global_load_dwordx4 v[116:119], v[0:1], off
	global_load_dwordx4 v[120:123], v[0:1], off offset:32
	global_load_dwordx4 v[124:127], v[0:1], off offset:64
	global_load_dwordx4 v[128:131], v[0:1], off offset:96
	v_add_u32_e32 v0, s87, v133
	v_mov_b32_e32 v89, v88
	v_cmp_gt_i32_e32 vcc, s66, v176
	v_cmp_lt_i32_e64 s[8:9], -1, v0
	v_mov_b32_e32 v90, v88
	v_mov_b32_e32 v91, v88
	v_mov_b64_e32 v[72:73], v[88:89]
	s_and_b64 vcc, vcc, s[8:9]
	v_mov_b32_e32 v64, 0
	v_mov_b64_e32 v[74:75], v[90:91]
	v_mov_b32_e32 v68, 0
	v_mov_b32_e32 v69, 0
	v_mov_b32_e32 v70, 0
	v_mov_b32_e32 v71, 0
	s_and_saveexec_b64 s[8:9], vcc
	s_cbranch_execz .LBB0_406
	v_mov_b64_e32 v[2:3], s[46:47]
	v_mad_u64_u32 v[0:1], vcc, v0, s90, v[2:3]
	v_mad_u64_u32 v[2:3], vcc, v0, s84, v[136:137]
	v_mov_b32_e32 v0, v3
	v_mad_u64_u32 v[0:1], vcc, v1, s84, v[0:1]
	v_mov_b32_e32 v3, v0
	s_lshl_b64 s[100:101], s[14:15], 15
	v_lshl_add_u64 v[0:1], s[100:101], 1, v[2:3]
	s_mov_b32 s11, s15
	s_lshl_b64 s[100:101], s[10:11], 15
	v_lshl_add_u64 v[2:3], s[100:101], 1, v[2:3]
	global_load_dwordx4 v[68:71], v[0:1], off
	global_load_dwordx4 v[72:75], v[2:3], off
.LBB0_406:
	s_or_b64 exec, exec, s[8:9]
	v_add_u32_e32 v0, s87, v178
	v_cmp_gt_i32_e32 vcc, s66, v177
	v_cmp_lt_i32_e64 s[8:9], -1, v0
	v_mov_b64_e32 v[76:77], v[88:89]
	s_and_b64 vcc, vcc, s[8:9]
	v_mov_b64_e32 v[78:79], v[90:91]
	v_mov_b32_e32 v65, 0
	v_mov_b32_e32 v66, 0
	v_mov_b32_e32 v67, 0
	s_and_saveexec_b64 s[8:9], vcc
	s_cbranch_execz .LBB0_408
	v_mov_b64_e32 v[2:3], s[46:47]
	v_mad_u64_u32 v[0:1], vcc, v0, s90, v[2:3]
	v_mad_u64_u32 v[2:3], vcc, v0, s84, v[136:137]
	v_mov_b32_e32 v0, v3
	v_mad_u64_u32 v[0:1], vcc, v1, s84, v[0:1]
	v_mov_b32_e32 v3, v0
	s_lshl_b64 s[100:101], s[14:15], 15
	v_lshl_add_u64 v[0:1], s[100:101], 1, v[2:3]
	s_mov_b32 s11, s15
	s_lshl_b64 s[100:101], s[10:11], 15
	v_lshl_add_u64 v[2:3], s[100:101], 1, v[2:3]
	global_load_dwordx4 v[64:67], v[0:1], off
	global_load_dwordx4 v[76:79], v[2:3], off
.LBB0_408:
	s_or_b64 exec, exec, s[8:9]
	v_add_u32_e32 v0, s87, v180
	v_mov_b32_e32 v89, v88
	v_cmp_gt_i32_e32 vcc, s66, v179
	v_cmp_lt_i32_e64 s[8:9], -1, v0
	v_mov_b32_e32 v90, v88
	v_mov_b32_e32 v91, v88
	v_mov_b64_e32 v[84:85], v[88:89]
	s_and_b64 vcc, vcc, s[8:9]
	v_mov_b32_e32 v92, 0
	v_mov_b64_e32 v[86:87], v[90:91]
	v_mov_b32_e32 v80, 0
	v_mov_b32_e32 v81, 0
	v_mov_b32_e32 v82, 0
	v_mov_b32_e32 v83, 0
	s_and_saveexec_b64 s[8:9], vcc
	s_cbranch_execz .LBB0_410
	v_mov_b64_e32 v[2:3], s[46:47]
	v_mad_u64_u32 v[0:1], vcc, v0, s90, v[2:3]
	v_mad_u64_u32 v[2:3], vcc, v0, s84, v[136:137]
	v_mov_b32_e32 v0, v3
	v_mad_u64_u32 v[0:1], vcc, v1, s84, v[0:1]
	v_mov_b32_e32 v3, v0
	s_lshl_b64 s[100:101], s[14:15], 15
	v_lshl_add_u64 v[0:1], s[100:101], 1, v[2:3]
	s_mov_b32 s11, s15
	s_lshl_b64 s[100:101], s[10:11], 15
	v_lshl_add_u64 v[2:3], s[100:101], 1, v[2:3]
	global_load_dwordx4 v[80:83], v[0:1], off
	global_load_dwordx4 v[84:87], v[2:3], off
.LBB0_410:
	s_or_b64 exec, exec, s[8:9]
	v_add_u32_e32 v0, s87, v182
	v_cmp_gt_i32_e32 vcc, s66, v181
	v_cmp_lt_i32_e64 s[8:9], -1, v0
	v_mov_b64_e32 v[98:99], v[90:91]
	s_and_b64 vcc, vcc, s[8:9]
	v_mov_b64_e32 v[96:97], v[88:89]
	v_mov_b32_e32 v93, 0
	v_mov_b32_e32 v94, 0
	v_mov_b32_e32 v95, 0
	s_and_saveexec_b64 s[8:9], vcc
	s_cbranch_execz .LBB0_412
	v_mov_b64_e32 v[2:3], s[46:47]
	v_mad_u64_u32 v[0:1], vcc, v0, s90, v[2:3]
	v_mad_u64_u32 v[2:3], vcc, v0, s84, v[136:137]
	v_mov_b32_e32 v0, v3
	v_mad_u64_u32 v[0:1], vcc, v1, s84, v[0:1]
	v_mov_b32_e32 v3, v0
	s_lshl_b64 s[100:101], s[14:15], 15
	v_lshl_add_u64 v[0:1], s[100:101], 1, v[2:3]
	s_mov_b32 s11, s15
	s_lshl_b64 s[100:101], s[10:11], 15
	v_lshl_add_u64 v[2:3], s[100:101], 1, v[2:3]
	global_load_dwordx4 v[92:95], v[0:1], off
	global_load_dwordx4 v[96:99], v[2:3], off
.LBB0_412:
	s_or_b64 exec, exec, s[8:9]
	v_add_u32_e32 v0, s87, v184
	v_mov_b32_e32 v90, v88
	v_mov_b32_e32 v91, v88
	v_cmp_gt_i32_e32 vcc, s66, v183
	v_cmp_lt_i32_e64 s[8:9], -1, v0
	v_mov_b32_e32 v89, v88
	v_mov_b64_e32 v[106:107], v[90:91]
	s_and_b64 vcc, vcc, s[8:9]
	v_mov_b32_e32 v111, 0
	v_mov_b64_e32 v[104:105], v[88:89]
	v_mov_b32_e32 v100, 0
	v_mov_b32_e32 v101, 0
	v_mov_b32_e32 v102, 0
	v_mov_b32_e32 v103, 0
	s_and_saveexec_b64 s[8:9], vcc
	s_cbranch_execz .LBB0_414
	v_mov_b64_e32 v[2:3], s[46:47]
	v_mad_u64_u32 v[0:1], vcc, v0, s90, v[2:3]
	v_mad_u64_u32 v[2:3], vcc, v0, s84, v[136:137]
	v_mov_b32_e32 v0, v3
	v_mad_u64_u32 v[0:1], vcc, v1, s84, v[0:1]
	v_mov_b32_e32 v3, v0
	s_lshl_b64 s[100:101], s[14:15], 15
	v_lshl_add_u64 v[0:1], s[100:101], 1, v[2:3]
	s_mov_b32 s11, s15
	s_lshl_b64 s[100:101], s[10:11], 15
	v_lshl_add_u64 v[2:3], s[100:101], 1, v[2:3]
	global_load_dwordx4 v[100:103], v[0:1], off
	global_load_dwordx4 v[104:107], v[2:3], off
.LBB0_414:
	s_or_b64 exec, exec, s[8:9]
	v_add_u32_e32 v0, s87, v186
	v_cmp_gt_i32_e32 vcc, s66, v185
	v_cmp_lt_i32_e64 s[8:9], -1, v0
	s_and_b64 vcc, vcc, s[8:9]
	v_mov_b32_e32 v110, 0
	v_mov_b32_e32 v109, 0
	v_mov_b32_e32 v108, 0
	v_mov_b32_e32 v115, 0
	v_mov_b32_e32 v114, 0
	v_mov_b32_e32 v113, 0
	v_mov_b32_e32 v112, 0
	s_and_saveexec_b64 s[8:9], vcc
	s_cbranch_execz .LBB0_416
	v_mov_b64_e32 v[2:3], s[46:47]
	v_mad_u64_u32 v[0:1], s[46:47], v0, s90, v[2:3]
	v_mad_u64_u32 v[2:3], s[46:47], v0, s84, v[136:137]
	v_mov_b32_e32 v0, v3
	v_mad_u64_u32 v[0:1], s[46:47], v1, s84, v[0:1]
	v_mov_b32_e32 v3, v0
	s_lshl_b64 s[100:101], s[14:15], 15
	v_lshl_add_u64 v[0:1], s[100:101], 1, v[2:3]
	s_mov_b32 s11, s15
	s_lshl_b64 s[100:101], s[10:11], 15
	v_lshl_add_u64 v[2:3], s[100:101], 1, v[2:3]
	global_load_dwordx4 v[108:111], v[0:1], off
	global_load_dwordx4 v[112:115], v[2:3], off

.LBB0_1077:
	s_lshr_b32 s98, s71, 6
	s_lshl_b32 s98, s98, 21
	s_bfe_u32 s100, s71, 0x10005
	s_lshl_b32 s100, s100, 5
	s_or_b32 s98, s98, s100
	s_add_i32 s0, s74, 0xfffff400
	s_lshl_b64 s[46:47], s[0:1], 1
	s_add_u32 s0, s56, s46
	s_addc_u32 s37, s57, s47
	s_ashr_i32 s75, s74, 31
	s_lshl_b64 s[46:47], s[74:75], 16
	s_add_u32 s46, s42, s46
	s_addc_u32 s47, s43, s47
	s_cmp_lt_i32 s40, 12
	s_cselect_b32 s98, s98, s71
	s_movk_i32 s100, 0x100
	s_cselect_b32 s100, 0x800000, s100
	s_mov_b32 s101, 0
	s_cselect_b32 s0, s46, s0
	v_lshl_add_u32 v164, v198, 3, s98
	s_cselect_b32 s37, s47, s37
	v_mov_b32_e32 v166, s0
	s_movk_i32 s0, 0x40
	v_mov_b32_e32 v167, s37
	s_cselect_b32 s0, s0, 0x800
	v_ashrrev_i32_e32 v165, 31, v164
	v_lshl_add_u32 v198, s36, 8, v199
	v_cvt_pk_bf16_f32 v212, v200, v202
	v_cvt_pk_bf16_f32 v213, v204, v207
	v_cvt_pk_bf16_f32 v214, v201, v203
	v_mov_b32_e32 v170, v173
	v_mov_b32_e32 v171, v173
	v_mov_b32_e32 v200, v173
	v_mov_b32_e32 v201, v173
	v_lshl_add_u64 v[164:165], v[164:165], 1, v[166:167]
	v_mad_i64_i32 v[166:167], s[36:37], s0, v198, 0
	v_cvt_pk_bf16_f32 v215, v205, v206
	v_mov_b32_e32 v168, v172
	v_mov_b32_e32 v169, v172
	v_pk_fma_f32 v[202:203], v[42:43], v[200:201], v[58:59]
	v_pk_fma_f32 v[204:205], v[40:41], v[170:171], v[56:57]
	v_mov_b32_e32 v173, v172
	v_pk_fma_f32 v[200:201], v[34:35], v[200:201], v[46:47]
	v_pk_fma_f32 v[170:171], v[32:33], v[170:171], v[44:45]
	v_lshl_add_u64 v[166:167], v[166:167], 1, v[164:165]
	v_pk_fma_f32 v[162:163], v[162:163], v[172:173], v[202:203]
	v_pk_fma_f32 v[160:161], v[160:161], v[168:169], v[204:205]
	v_pk_fma_f32 v[158:159], v[158:159], v[172:173], v[200:201]
	v_pk_fma_f32 v[156:157], v[156:157], v[168:169], v[170:171]
	s_cmp_gt_i32 s61, 1
	s_mov_b64 s[36:37], -1
	global_store_dwordx4 v[166:167], v[212:215], off
	s_cbranch_scc0 .LBB0_1079
	v_mul_f32_e32 v199, 0xbfb8aa3b, v163
	v_mul_f32_e32 v168, 0xbfb8aa3b, v160
	v_mul_f32_e32 v169, 0xbfb8aa3b, v156
	v_mul_f32_e32 v170, 0xbfb8aa3b, v161
	v_mul_f32_e32 v171, 0xbfb8aa3b, v157
	v_mul_f32_e32 v172, 0xbfb8aa3b, v162
	v_mul_f32_e32 v173, 0xbfb8aa3b, v158
	v_exp_f32_e32 v199, v199
	v_mul_f32_e32 v200, 0xbfb8aa3b, v159
	v_exp_f32_e32 v168, v168
	v_exp_f32_e32 v169, v169
	v_exp_f32_e32 v170, v170
	v_exp_f32_e32 v171, v171
	v_exp_f32_e32 v172, v172
	v_exp_f32_e32 v173, v173
	v_exp_f32_e32 v201, v200
	v_add_f32_e32 v199, 1.0, v199
	v_add_f32_e32 v168, 1.0, v168
	v_add_f32_e32 v169, 1.0, v169
	v_add_f32_e32 v170, 1.0, v170
	v_add_f32_e32 v171, 1.0, v171
	v_add_f32_e32 v172, 1.0, v172
	v_add_f32_e32 v173, 1.0, v173
	v_rcp_f32_e32 v200, v199
	v_add_f32_e32 v199, 1.0, v201
	v_rcp_f32_e32 v168, v168
	v_rcp_f32_e32 v169, v169
	v_rcp_f32_e32 v170, v170
	v_rcp_f32_e32 v171, v171
	v_rcp_f32_e32 v172, v172
	v_rcp_f32_e32 v173, v173
	v_rcp_f32_e32 v199, v199
	s_mov_b64 s[36:37], 0

.LBB0_1083:
	v_cvt_pk_bf16_f32 v156, v168, v170
	v_cvt_pk_bf16_f32 v157, v172, v200
	v_cvt_pk_bf16_f32 v158, v169, v171
	v_cvt_pk_bf16_f32 v159, v173, v199
	v_lshl_add_u64 v[234:235], v[166:167], 0, s[100:101]
	global_store_dwordx4 v[234:235], v[156:159], off
	s_cmp_gt_i32 s61, 1
	s_mov_b64 s[36:37], -1
	v_pk_fma_f32 v[156:157], v[68:69], v[174:175], v[72:73] op_sel:[0,1,0]
	v_pk_fma_f32 v[158:159], v[70:71], v[174:175], v[74:75] op_sel:[0,1,0]
	v_pk_fma_f32 v[152:153], v[152:153], v[174:175], v[156:157] op_sel_hi:[1,0,1]
	v_pk_fma_f32 v[154:155], v[154:155], v[174:175], v[158:159] op_sel_hi:[1,0,1]
	v_pk_fma_f32 v[156:157], v[60:61], v[174:175], v[64:65] op_sel:[0,1,0]
	v_pk_fma_f32 v[158:159], v[62:63], v[174:175], v[66:67] op_sel:[0,1,0]
	v_pk_fma_f32 v[148:149], v[148:149], v[174:175], v[156:157] op_sel_hi:[1,0,1]
	v_pk_fma_f32 v[150:151], v[150:151], v[174:175], v[158:159] op_sel_hi:[1,0,1]
	s_cbranch_scc0 .LBB0_1085
	v_mul_f32_e32 v162, 0xbfb8aa3b, v155
	v_mul_f32_e32 v156, 0xbfb8aa3b, v152
	v_mul_f32_e32 v157, 0xbfb8aa3b, v148
	v_mul_f32_e32 v158, 0xbfb8aa3b, v153
	v_mul_f32_e32 v159, 0xbfb8aa3b, v149
	v_mul_f32_e32 v160, 0xbfb8aa3b, v154
	v_mul_f32_e32 v161, 0xbfb8aa3b, v150
	v_exp_f32_e32 v162, v162
	v_mul_f32_e32 v163, 0xbfb8aa3b, v151
	v_exp_f32_e32 v156, v156
	v_exp_f32_e32 v157, v157
	v_exp_f32_e32 v158, v158
	v_exp_f32_e32 v159, v159
	v_exp_f32_e32 v160, v160
	v_exp_f32_e32 v161, v161
	v_exp_f32_e32 v166, v163
	v_add_f32_e32 v162, 1.0, v162
	v_add_f32_e32 v156, 1.0, v156
	v_add_f32_e32 v157, 1.0, v157
	v_add_f32_e32 v158, 1.0, v158
	v_add_f32_e32 v159, 1.0, v159
	v_add_f32_e32 v160, 1.0, v160
	v_add_f32_e32 v161, 1.0, v161
	v_rcp_f32_e32 v163, v162
	v_add_f32_e32 v162, 1.0, v166
	v_rcp_f32_e32 v156, v156
	v_rcp_f32_e32 v157, v157
	v_rcp_f32_e32 v158, v158
	v_rcp_f32_e32 v159, v159
	v_rcp_f32_e32 v160, v160
	v_rcp_f32_e32 v161, v161
	v_rcp_f32_e32 v162, v162
	s_mov_b64 s[36:37], 0

.LBB0_1095:
	v_cvt_pk_bf16_f32 v140, v150, v152
	v_cvt_pk_bf16_f32 v141, v154, v157
	v_cvt_pk_bf16_f32 v142, v151, v153
	v_cvt_pk_bf16_f32 v143, v155, v156
	v_lshl_add_u64 v[234:235], v[148:149], 0, s[100:101]
	global_store_dwordx4 v[234:235], v[140:143], off
	s_cmp_gt_i32 s61, 1
	s_mov_b64 s[36:37], -1
	v_pk_fma_f32 v[140:141], v[68:69], v[136:137], v[72:73] op_sel:[0,1,0]
	v_pk_fma_f32 v[142:143], v[70:71], v[136:137], v[74:75] op_sel:[0,1,0]
	v_pk_fma_f32 v[132:133], v[132:133], v[136:137], v[140:141] op_sel_hi:[1,0,1]
	v_pk_fma_f32 v[134:135], v[134:135], v[136:137], v[142:143] op_sel_hi:[1,0,1]
	v_pk_fma_f32 v[140:141], v[60:61], v[136:137], v[64:65] op_sel:[0,1,0]
	v_pk_fma_f32 v[142:143], v[62:63], v[136:137], v[66:67] op_sel:[0,1,0]
	v_pk_fma_f32 v[128:129], v[128:129], v[136:137], v[140:141] op_sel_hi:[1,0,1]
	v_pk_fma_f32 v[130:131], v[130:131], v[136:137], v[142:143] op_sel_hi:[1,0,1]
	s_cbranch_scc0 .LBB0_1097
	v_mul_f32_e32 v146, 0xbfb8aa3b, v135
	v_mul_f32_e32 v140, 0xbfb8aa3b, v132
	v_mul_f32_e32 v141, 0xbfb8aa3b, v128
	v_mul_f32_e32 v142, 0xbfb8aa3b, v133
	v_mul_f32_e32 v143, 0xbfb8aa3b, v129
	v_mul_f32_e32 v144, 0xbfb8aa3b, v134
	v_mul_f32_e32 v145, 0xbfb8aa3b, v130
	v_exp_f32_e32 v146, v146
	v_mul_f32_e32 v147, 0xbfb8aa3b, v131
	v_exp_f32_e32 v140, v140
	v_exp_f32_e32 v141, v141
	v_exp_f32_e32 v142, v142
	v_exp_f32_e32 v143, v143
	v_exp_f32_e32 v144, v144
	v_exp_f32_e32 v145, v145
	v_exp_f32_e32 v148, v147
	v_add_f32_e32 v146, 1.0, v146
	v_add_f32_e32 v140, 1.0, v140
	v_add_f32_e32 v141, 1.0, v141
	v_add_f32_e32 v142, 1.0, v142
	v_add_f32_e32 v143, 1.0, v143
	v_add_f32_e32 v144, 1.0, v144
	v_add_f32_e32 v145, 1.0, v145
	v_rcp_f32_e32 v147, v146
	v_add_f32_e32 v146, 1.0, v148
	v_rcp_f32_e32 v140, v140
	v_rcp_f32_e32 v141, v141
	v_rcp_f32_e32 v142, v142
	v_rcp_f32_e32 v143, v143
	v_rcp_f32_e32 v144, v144
	v_rcp_f32_e32 v145, v145
	v_rcp_f32_e32 v146, v146
	s_mov_b64 s[36:37], 0

.LBB0_1107:
	v_cvt_pk_bf16_f32 v120, v130, v132
	v_cvt_pk_bf16_f32 v121, v134, v137
	v_cvt_pk_bf16_f32 v122, v131, v133
	v_cvt_pk_bf16_f32 v123, v135, v136
	v_lshl_add_u64 v[234:235], v[128:129], 0, s[100:101]
	global_store_dwordx4 v[234:235], v[120:123], off
	s_cmp_gt_i32 s61, 1
	s_mov_b64 s[36:37], -1
	v_pk_fma_f32 v[120:121], v[68:69], v[138:139], v[72:73] op_sel:[0,1,0]
	v_pk_fma_f32 v[122:123], v[70:71], v[138:139], v[74:75] op_sel:[0,1,0]
	v_pk_fma_f32 v[116:117], v[116:117], v[138:139], v[120:121] op_sel_hi:[1,0,1]
	v_pk_fma_f32 v[118:119], v[118:119], v[138:139], v[122:123] op_sel_hi:[1,0,1]
	v_pk_fma_f32 v[120:121], v[60:61], v[138:139], v[64:65] op_sel:[0,1,0]
	v_pk_fma_f32 v[122:123], v[62:63], v[138:139], v[66:67] op_sel:[0,1,0]
	v_pk_fma_f32 v[112:113], v[112:113], v[138:139], v[120:121] op_sel_hi:[1,0,1]
	v_pk_fma_f32 v[114:115], v[114:115], v[138:139], v[122:123] op_sel_hi:[1,0,1]
	s_cbranch_scc0 .LBB0_1109
	v_mul_f32_e32 v126, 0xbfb8aa3b, v119
	v_mul_f32_e32 v120, 0xbfb8aa3b, v116
	v_mul_f32_e32 v121, 0xbfb8aa3b, v112
	v_mul_f32_e32 v122, 0xbfb8aa3b, v117
	v_mul_f32_e32 v123, 0xbfb8aa3b, v113
	v_mul_f32_e32 v124, 0xbfb8aa3b, v118
	v_mul_f32_e32 v125, 0xbfb8aa3b, v114
	v_exp_f32_e32 v126, v126
	v_mul_f32_e32 v127, 0xbfb8aa3b, v115
	v_exp_f32_e32 v120, v120
	v_exp_f32_e32 v121, v121
	v_exp_f32_e32 v122, v122
	v_exp_f32_e32 v123, v123
	v_exp_f32_e32 v124, v124
	v_exp_f32_e32 v125, v125
	v_exp_f32_e32 v128, v127
	v_add_f32_e32 v126, 1.0, v126
	v_add_f32_e32 v120, 1.0, v120
	v_add_f32_e32 v121, 1.0, v121
	v_add_f32_e32 v122, 1.0, v122
	v_add_f32_e32 v123, 1.0, v123
	v_add_f32_e32 v124, 1.0, v124
	v_add_f32_e32 v125, 1.0, v125
	v_rcp_f32_e32 v127, v126
	v_add_f32_e32 v126, 1.0, v128
	v_rcp_f32_e32 v120, v120
	v_rcp_f32_e32 v121, v121
	v_rcp_f32_e32 v122, v122
	v_rcp_f32_e32 v123, v123
	v_rcp_f32_e32 v124, v124
	v_rcp_f32_e32 v125, v125
	v_rcp_f32_e32 v126, v126
	s_mov_b64 s[36:37], 0

.LBB0_1119:
	v_cvt_pk_bf16_f32 v104, v114, v116
	v_cvt_pk_bf16_f32 v105, v118, v121
	v_cvt_pk_bf16_f32 v106, v115, v117
	v_cvt_pk_bf16_f32 v107, v119, v120
	v_lshl_add_u64 v[234:235], v[112:113], 0, s[100:101]
	global_store_dwordx4 v[234:235], v[104:107], off
	s_cmp_gt_i32 s61, 1
	s_mov_b64 s[36:37], -1
	v_pk_fma_f32 v[104:105], v[68:69], v[100:101], v[72:73] op_sel:[0,1,0]
	v_pk_fma_f32 v[106:107], v[70:71], v[100:101], v[74:75] op_sel:[0,1,0]
	v_pk_fma_f32 v[96:97], v[96:97], v[100:101], v[104:105] op_sel_hi:[1,0,1]
	v_pk_fma_f32 v[98:99], v[98:99], v[100:101], v[106:107] op_sel_hi:[1,0,1]
	v_pk_fma_f32 v[104:105], v[60:61], v[100:101], v[64:65] op_sel:[0,1,0]
	v_pk_fma_f32 v[106:107], v[62:63], v[100:101], v[66:67] op_sel:[0,1,0]
	v_pk_fma_f32 v[92:93], v[92:93], v[100:101], v[104:105] op_sel_hi:[1,0,1]
	v_pk_fma_f32 v[94:95], v[94:95], v[100:101], v[106:107] op_sel_hi:[1,0,1]
	s_cbranch_scc0 .LBB0_1121
	v_mul_f32_e32 v110, 0xbfb8aa3b, v99
	v_mul_f32_e32 v104, 0xbfb8aa3b, v96
	v_mul_f32_e32 v105, 0xbfb8aa3b, v92
	v_mul_f32_e32 v106, 0xbfb8aa3b, v97
	v_mul_f32_e32 v107, 0xbfb8aa3b, v93
	v_mul_f32_e32 v108, 0xbfb8aa3b, v98
	v_mul_f32_e32 v109, 0xbfb8aa3b, v94
	v_exp_f32_e32 v110, v110
	v_mul_f32_e32 v111, 0xbfb8aa3b, v95
	v_exp_f32_e32 v104, v104
	v_exp_f32_e32 v105, v105
	v_exp_f32_e32 v106, v106
	v_exp_f32_e32 v107, v107
	v_exp_f32_e32 v108, v108
	v_exp_f32_e32 v109, v109
	v_exp_f32_e32 v112, v111
	v_add_f32_e32 v110, 1.0, v110
	v_add_f32_e32 v104, 1.0, v104
	v_add_f32_e32 v105, 1.0, v105
	v_add_f32_e32 v106, 1.0, v106
	v_add_f32_e32 v107, 1.0, v107
	v_add_f32_e32 v108, 1.0, v108
	v_add_f32_e32 v109, 1.0, v109
	v_rcp_f32_e32 v111, v110
	v_add_f32_e32 v110, 1.0, v112
	v_rcp_f32_e32 v104, v104
	v_rcp_f32_e32 v105, v105
	v_rcp_f32_e32 v106, v106
	v_rcp_f32_e32 v107, v107
	v_rcp_f32_e32 v108, v108
	v_rcp_f32_e32 v109, v109
	v_rcp_f32_e32 v110, v110
	s_mov_b64 s[36:37], 0

.LBB0_1131:
	v_cvt_pk_bf16_f32 v84, v94, v96
	v_cvt_pk_bf16_f32 v85, v98, v101
	v_cvt_pk_bf16_f32 v86, v95, v97
	v_cvt_pk_bf16_f32 v87, v99, v100
	v_lshl_add_u64 v[234:235], v[92:93], 0, s[100:101]
	global_store_dwordx4 v[234:235], v[84:87], off
	s_cmp_gt_i32 s61, 1
	s_mov_b64 s[36:37], -1
	v_pk_fma_f32 v[84:85], v[68:69], v[102:103], v[72:73] op_sel:[0,1,0]
	v_pk_fma_f32 v[86:87], v[70:71], v[102:103], v[74:75] op_sel:[0,1,0]
	v_pk_fma_f32 v[80:81], v[80:81], v[102:103], v[84:85] op_sel_hi:[1,0,1]
	v_pk_fma_f32 v[82:83], v[82:83], v[102:103], v[86:87] op_sel_hi:[1,0,1]
	v_pk_fma_f32 v[84:85], v[60:61], v[102:103], v[64:65] op_sel:[0,1,0]
	v_pk_fma_f32 v[86:87], v[62:63], v[102:103], v[66:67] op_sel:[0,1,0]
	v_pk_fma_f32 v[76:77], v[76:77], v[102:103], v[84:85] op_sel_hi:[1,0,1]
	v_pk_fma_f32 v[78:79], v[78:79], v[102:103], v[86:87] op_sel_hi:[1,0,1]
	s_cbranch_scc0 .LBB0_1133
	v_mul_f32_e32 v90, 0xbfb8aa3b, v83
	v_mul_f32_e32 v84, 0xbfb8aa3b, v80
	v_mul_f32_e32 v85, 0xbfb8aa3b, v76
	v_mul_f32_e32 v86, 0xbfb8aa3b, v81
	v_mul_f32_e32 v87, 0xbfb8aa3b, v77
	v_mul_f32_e32 v88, 0xbfb8aa3b, v82
	v_mul_f32_e32 v89, 0xbfb8aa3b, v78
	v_exp_f32_e32 v90, v90
	v_mul_f32_e32 v91, 0xbfb8aa3b, v79
	v_exp_f32_e32 v84, v84
	v_exp_f32_e32 v85, v85
	v_exp_f32_e32 v86, v86
	v_exp_f32_e32 v87, v87
	v_exp_f32_e32 v88, v88
	v_exp_f32_e32 v89, v89
	v_exp_f32_e32 v92, v91
	v_add_f32_e32 v90, 1.0, v90
	v_add_f32_e32 v84, 1.0, v84
	v_add_f32_e32 v85, 1.0, v85
	v_add_f32_e32 v86, 1.0, v86
	v_add_f32_e32 v87, 1.0, v87
	v_add_f32_e32 v88, 1.0, v88
	v_add_f32_e32 v89, 1.0, v89
	v_rcp_f32_e32 v91, v90
	v_add_f32_e32 v90, 1.0, v92
	v_rcp_f32_e32 v84, v84
	v_rcp_f32_e32 v85, v85
	v_rcp_f32_e32 v86, v86
	v_rcp_f32_e32 v87, v87
	v_rcp_f32_e32 v88, v88
	v_rcp_f32_e32 v89, v89
	v_rcp_f32_e32 v90, v90
	s_mov_b64 s[36:37], 0

.LBB0_1143:
	v_cvt_pk_bf16_f32 v36, v78, v80
	v_cvt_pk_bf16_f32 v37, v82, v85
	v_cvt_pk_bf16_f32 v38, v79, v81
	v_cvt_pk_bf16_f32 v39, v83, v84
	v_lshl_add_u64 v[234:235], v[76:77], 0, s[100:101]
	global_store_dwordx4 v[234:235], v[36:39], off
	s_cmp_gt_i32 s61, 1
	s_mov_b64 s[36:37], -1
	v_pk_fma_f32 v[36:37], v[68:69], v[48:49], v[72:73] op_sel:[0,1,0]
	v_pk_fma_f32 v[38:39], v[70:71], v[48:49], v[74:75] op_sel:[0,1,0]
	v_pk_fma_f32 v[28:29], v[28:29], v[48:49], v[36:37] op_sel_hi:[1,0,1]
	v_pk_fma_f32 v[30:31], v[30:31], v[48:49], v[38:39] op_sel_hi:[1,0,1]
	v_pk_fma_f32 v[36:37], v[60:61], v[48:49], v[64:65] op_sel:[0,1,0]
	v_pk_fma_f32 v[38:39], v[62:63], v[48:49], v[66:67] op_sel:[0,1,0]
	v_pk_fma_f32 v[24:25], v[24:25], v[48:49], v[36:37] op_sel_hi:[1,0,1]
	v_pk_fma_f32 v[26:27], v[26:27], v[48:49], v[38:39] op_sel_hi:[1,0,1]
	s_cbranch_scc0 .LBB0_1145
	v_mul_f32_e32 v54, 0xbfb8aa3b, v31
	v_mul_f32_e32 v36, 0xbfb8aa3b, v28
	v_mul_f32_e32 v37, 0xbfb8aa3b, v24
	v_mul_f32_e32 v38, 0xbfb8aa3b, v29
	v_mul_f32_e32 v39, 0xbfb8aa3b, v25
	v_mul_f32_e32 v52, 0xbfb8aa3b, v30
	v_mul_f32_e32 v53, 0xbfb8aa3b, v26
	v_exp_f32_e32 v54, v54
	v_mul_f32_e32 v55, 0xbfb8aa3b, v27
	v_exp_f32_e32 v36, v36
	v_exp_f32_e32 v37, v37
	v_exp_f32_e32 v38, v38
	v_exp_f32_e32 v39, v39
	v_exp_f32_e32 v52, v52
	v_exp_f32_e32 v53, v53
	v_exp_f32_e32 v76, v55
	v_add_f32_e32 v54, 1.0, v54
	v_add_f32_e32 v36, 1.0, v36
	v_add_f32_e32 v37, 1.0, v37
	v_add_f32_e32 v38, 1.0, v38
	v_add_f32_e32 v39, 1.0, v39
	v_add_f32_e32 v52, 1.0, v52
	v_add_f32_e32 v53, 1.0, v53
	v_rcp_f32_e32 v55, v54
	v_add_f32_e32 v54, 1.0, v76
	v_rcp_f32_e32 v36, v36
	v_rcp_f32_e32 v37, v37
	v_rcp_f32_e32 v38, v38
	v_rcp_f32_e32 v39, v39
	v_rcp_f32_e32 v52, v52
	v_rcp_f32_e32 v53, v53
	v_rcp_f32_e32 v54, v54
	s_mov_b64 s[36:37], 0

.LBB0_1155:
	v_cvt_pk_bf16_f32 v16, v26, v28
	v_cvt_pk_bf16_f32 v17, v30, v37
	v_cvt_pk_bf16_f32 v18, v27, v29
	v_cvt_pk_bf16_f32 v19, v31, v36
	v_lshl_add_u64 v[234:235], v[24:25], 0, s[100:101]
	global_store_dwordx4 v[234:235], v[16:19], off
	s_cmp_gt_i32 s61, 1
	s_mov_b64 s[36:37], -1
	v_pk_fma_f32 v[16:17], v[68:69], v[50:51], v[72:73] op_sel:[0,1,0]
	v_pk_fma_f32 v[18:19], v[70:71], v[50:51], v[74:75] op_sel:[0,1,0]
	v_pk_fma_f32 v[12:13], v[12:13], v[50:51], v[16:17] op_sel_hi:[1,0,1]
	v_pk_fma_f32 v[14:15], v[14:15], v[50:51], v[18:19] op_sel_hi:[1,0,1]
	v_pk_fma_f32 v[16:17], v[60:61], v[50:51], v[64:65] op_sel:[0,1,0]
	v_pk_fma_f32 v[18:19], v[62:63], v[50:51], v[66:67] op_sel:[0,1,0]
	v_pk_fma_f32 v[8:9], v[8:9], v[50:51], v[16:17] op_sel_hi:[1,0,1]
	v_pk_fma_f32 v[10:11], v[10:11], v[50:51], v[18:19] op_sel_hi:[1,0,1]
	s_cbranch_scc0 .LBB0_1157
	v_mul_f32_e32 v22, 0xbfb8aa3b, v15
	v_mul_f32_e32 v16, 0xbfb8aa3b, v12
	v_mul_f32_e32 v17, 0xbfb8aa3b, v8
	v_mul_f32_e32 v18, 0xbfb8aa3b, v13
	v_mul_f32_e32 v19, 0xbfb8aa3b, v9
	v_mul_f32_e32 v20, 0xbfb8aa3b, v14
	v_mul_f32_e32 v21, 0xbfb8aa3b, v10
	v_exp_f32_e32 v22, v22
	v_mul_f32_e32 v23, 0xbfb8aa3b, v11
	v_exp_f32_e32 v16, v16
	v_exp_f32_e32 v17, v17
	v_exp_f32_e32 v18, v18
	v_exp_f32_e32 v19, v19
	v_exp_f32_e32 v20, v20
	v_exp_f32_e32 v21, v21
	v_exp_f32_e32 v24, v23
	v_add_f32_e32 v22, 1.0, v22
	v_add_f32_e32 v16, 1.0, v16
	v_add_f32_e32 v17, 1.0, v17
	v_add_f32_e32 v18, 1.0, v18
	v_add_f32_e32 v19, 1.0, v19
	v_add_f32_e32 v20, 1.0, v20
	v_add_f32_e32 v21, 1.0, v21
	v_rcp_f32_e32 v23, v22
	v_add_f32_e32 v22, 1.0, v24
	v_rcp_f32_e32 v16, v16
	v_rcp_f32_e32 v17, v17
	v_rcp_f32_e32 v18, v18
	v_rcp_f32_e32 v19, v19
	v_rcp_f32_e32 v20, v20
	v_rcp_f32_e32 v21, v21
	v_rcp_f32_e32 v22, v22
	s_mov_b64 s[36:37], 0

.LBB0_1167:
	s_andn2_b64 vcc, exec, s[8:9]
	s_mov_b64 s[8:9], -1
	v_cvt_pk_bf16_f32 v0, v10, v12
	v_cvt_pk_bf16_f32 v1, v14, v17
	v_cvt_pk_bf16_f32 v2, v11, v13
	v_cvt_pk_bf16_f32 v3, v15, v16
	v_lshl_add_u64 v[234:235], v[8:9], 0, s[100:101]
	global_store_dwordx4 v[234:235], v[0:3], off
	s_mov_b32 s99, 1
	s_cbranch_vccnz .LBB0_1062
	s_andn2_b64 vcc, exec, s[4:5]
	s_cbranch_vccnz .LBB0_1061
	s_barrier
	s_branch .LBB0_1061

.LBB0_1228:
	v_readlane_b32 s14, v255, 16
	v_bfe_u32 v7, v6, 5, 1
	v_readlane_b32 s15, v255, 17
	v_and_b32_e32 v139, 31, v6
	s_and_b64 vcc, exec, s[14:15]
	v_lshlrev_b32_e32 v132, 4, v7
	v_lshlrev_b32_e32 v8, 4, v6
	v_ashrrev_i32_e32 v176, 3, v6
	s_cbranch_vccnz .LBB0_1242
	s_ashr_i32 s5, s4, 31
	s_lshl_b64 s[14:15], s[4:5], 14
	s_or_b32 s14, s14, s65
	v_add_u32_e32 v2, s7, v139
	v_mov_b64_e32 v[0:1], s[14:15]
	v_mad_i64_i32 v[0:1], s[36:37], v2, s1, v[0:1]
	s_movk_i32 s5, 0x80
	v_mov_b64_e32 v[2:3], s[42:43]
	v_mad_u64_u32 v[2:3], s[36:37], v0, s5, v[2:3]
	v_mov_b32_e32 v0, v3
	v_mad_u64_u32 v[0:1], s[36:37], v1, s5, v[0:1]
	v_mov_b32_e32 v3, v0
	s_ashr_i32 s9, s8, 31
	v_mov_b32_e32 v64, 0
	s_lshl_b64 s[100:101], s[8:9], 15
	v_lshl_add_u64 v[0:1], s[100:101], 1, v[2:3]
	v_mov_b32_e32 v133, v64
	v_lshl_add_u64 v[0:1], v[0:1], 0, v[132:133]
	global_load_dwordx4 v[48:51], v[0:1], off
	global_load_dwordx4 v[52:55], v[0:1], off offset:32
	global_load_dwordx4 v[56:59], v[0:1], off offset:64
	global_load_dwordx4 v[60:63], v[0:1], off offset:96
	v_and_b32_e32 v0, 0x70, v8
	v_mov_b32_e32 v1, v64
	v_lshl_add_u64 v[4:5], s[42:43], 0, v[0:1]
	v_add_u32_e32 v0, s79, v176
	v_add_u32_e32 v0, 0xffffff80, v0
	v_mov_b32_e32 v76, 0
	v_mov_b32_e32 v77, v64
	v_cmp_gt_i32_e32 vcc, s64, v176
	v_cmp_lt_i32_e64 s[8:9], -1, v0
	v_mov_b32_e32 v78, v64
	v_mov_b32_e32 v79, v64
	v_mov_b64_e32 v[72:73], v[76:77]
	s_and_b64 s[36:37], vcc, s[8:9]
	s_mov_b32 s11, 0
	v_mov_b64_e32 v[74:75], v[78:79]
	v_mov_b32_e32 v68, 0
	v_mov_b32_e32 v69, 0
	v_mov_b32_e32 v70, 0
	v_mov_b32_e32 v71, 0
	s_and_saveexec_b64 s[8:9], s[36:37]
	s_cbranch_execz .LBB0_1231
	v_mov_b64_e32 v[2:3], s[14:15]
	v_mad_u64_u32 v[0:1], s[36:37], v0, s1, v[2:3]
	v_mad_u64_u32 v[2:3], s[36:37], v0, s5, v[4:5]
	v_mov_b32_e32 v0, v3
	v_mad_u64_u32 v[0:1], s[36:37], v1, s5, v[0:1]
	v_mov_b32_e32 v3, v0
	s_lshl_b64 s[100:101], s[10:11], 15
	v_lshl_add_u64 v[0:1], s[100:101], 1, v[2:3]
	s_mov_b32 s13, s11
	s_lshl_b64 s[100:101], s[12:13], 15
	v_lshl_add_u64 v[2:3], s[100:101], 1, v[2:3]
	global_load_dwordx4 v[68:71], v[0:1], off
	global_load_dwordx4 v[72:75], v[2:3], off
.LBB0_1231:
	s_or_b64 exec, exec, s[8:9]
	v_add_u32_e32 v0, 0x200, v6
	v_ashrrev_i32_e32 v1, 3, v0
	v_add_u32_e32 v0, s79, v1
	v_add_u32_e32 v0, 0xffffff80, v0
	v_cmp_gt_i32_e32 vcc, s64, v1
	v_cmp_lt_i32_e64 s[8:9], -1, v0
	s_and_b64 s[36:37], vcc, s[8:9]
	v_mov_b32_e32 v65, 0
	v_mov_b32_e32 v66, 0
	v_mov_b32_e32 v67, 0
	s_and_saveexec_b64 s[8:9], s[36:37]
	s_cbranch_execz .LBB0_1233
	v_mov_b64_e32 v[2:3], s[14:15]
	v_mad_u64_u32 v[0:1], s[36:37], v0, s1, v[2:3]
	v_mad_u64_u32 v[2:3], s[36:37], v0, s5, v[4:5]
	v_mov_b32_e32 v0, v3
	v_mad_u64_u32 v[0:1], s[36:37], v1, s5, v[0:1]
	v_mov_b32_e32 v3, v0
	s_lshl_b64 s[100:101], s[10:11], 15
	v_lshl_add_u64 v[0:1], s[100:101], 1, v[2:3]
	s_mov_b32 s13, s11
	s_lshl_b64 s[100:101], s[12:13], 15
	v_lshl_add_u64 v[2:3], s[100:101], 1, v[2:3]
	global_load_dwordx4 v[64:67], v[0:1], off
	global_load_dwordx4 v[76:79], v[2:3], off
.LBB0_1233:
	s_or_b64 exec, exec, s[8:9]
	v_add_u32_e32 v0, 0x400, v6
	v_ashrrev_i32_e32 v1, 3, v0
	v_add_u32_e32 v0, s79, v1
	v_mov_b32_e32 v96, 0
	v_add_u32_e32 v0, 0xffffff80, v0
	v_mov_b32_e32 v97, v96
	v_cmp_gt_i32_e32 vcc, s64, v1
	v_cmp_lt_i32_e64 s[8:9], -1, v0
	v_mov_b32_e32 v98, v96
	v_mov_b32_e32 v99, v96
	v_mov_b64_e32 v[84:85], v[96:97]
	s_and_b64 s[36:37], vcc, s[8:9]
	v_mov_b64_e32 v[86:87], v[98:99]
	v_mov_b32_e32 v80, v96
	v_mov_b32_e32 v81, v96
	v_mov_b32_e32 v82, v96
	v_mov_b32_e32 v83, v96
	s_and_saveexec_b64 s[8:9], s[36:37]
	s_cbranch_execz .LBB0_1235
	v_mov_b64_e32 v[2:3], s[14:15]
	v_mad_u64_u32 v[0:1], s[36:37], v0, s1, v[2:3]
	v_mad_u64_u32 v[2:3], s[36:37], v0, s5, v[4:5]
	v_mov_b32_e32 v0, v3
	v_mad_u64_u32 v[0:1], s[36:37], v1, s5, v[0:1]
	v_mov_b32_e32 v3, v0
	s_lshl_b64 s[100:101], s[10:11], 15
	v_lshl_add_u64 v[0:1], s[100:101], 1, v[2:3]
	s_mov_b32 s13, s11
	s_lshl_b64 s[100:101], s[12:13], 15
	v_lshl_add_u64 v[2:3], s[100:101], 1, v[2:3]
	global_load_dwordx4 v[80:83], v[0:1], off
	global_load_dwordx4 v[84:87], v[2:3], off
.LBB0_1235:
	s_or_b64 exec, exec, s[8:9]
	v_add_u32_e32 v0, 0x600, v6
	v_ashrrev_i32_e32 v1, 3, v0
	v_add_u32_e32 v0, s79, v1
	v_add_u32_e32 v0, 0xffffff80, v0
	v_cmp_gt_i32_e32 vcc, s64, v1
	v_cmp_lt_i32_e64 s[8:9], -1, v0
	s_and_b64 s[36:37], vcc, s[8:9]
	v_mov_b32_e32 v92, v96
	v_mov_b32_e32 v93, v96
	v_mov_b32_e32 v94, v96
	v_mov_b32_e32 v95, v96
	s_and_saveexec_b64 s[8:9], s[36:37]
	s_cbranch_execz .LBB0_1237
	v_mov_b64_e32 v[2:3], s[14:15]
	v_mad_u64_u32 v[0:1], s[36:37], v0, s1, v[2:3]
	v_mad_u64_u32 v[2:3], s[36:37], v0, s5, v[4:5]
	v_mov_b32_e32 v0, v3
	v_mad_u64_u32 v[0:1], s[36:37], v1, s5, v[0:1]
	v_mov_b32_e32 v3, v0
	s_lshl_b64 s[100:101], s[10:11], 15
	v_lshl_add_u64 v[0:1], s[100:101], 1, v[2:3]
	s_mov_b32 s13, s11
	s_lshl_b64 s[100:101], s[12:13], 15
	v_lshl_add_u64 v[2:3], s[100:101], 1, v[2:3]
	global_load_dwordx4 v[92:95], v[0:1], off
	global_load_dwordx4 v[96:99], v[2:3], off
.LBB0_1237:
	s_or_b64 exec, exec, s[8:9]
	v_add_u32_e32 v0, 0x800, v6
	v_ashrrev_i32_e32 v0, 3, v0
	v_add_u32_e32 v1, s79, v0
	v_cmp_gt_i32_e32 vcc, s64, v0
	v_mov_b32_e32 v0, 0
	v_add_u32_e32 v9, 0xffffff80, v1
	v_mov_b32_e32 v2, v0
	v_mov_b32_e32 v3, v0
	v_cmp_lt_i32_e64 s[8:9], -1, v9
	v_mov_b32_e32 v1, v0
	v_mov_b64_e32 v[106:107], v[2:3]
	s_and_b64 s[36:37], vcc, s[8:9]
	v_mov_b64_e32 v[104:105], v[0:1]
	v_mov_b32_e32 v100, 0
	v_mov_b32_e32 v101, 0
	v_mov_b32_e32 v102, 0
	v_mov_b32_e32 v103, 0
	s_and_saveexec_b64 s[8:9], s[36:37]
	s_cbranch_execz .LBB0_1239
	v_mov_b64_e32 v[2:3], s[14:15]
	v_mad_u64_u32 v[2:3], s[36:37], v9, s1, v[2:3]
	v_mad_u64_u32 v[10:11], s[36:37], v2, s5, v[4:5]
	v_mov_b32_e32 v2, v11
	v_mad_u64_u32 v[2:3], s[36:37], v3, s5, v[2:3]
	v_mov_b32_e32 v11, v2
	s_lshl_b64 s[100:101], s[10:11], 15
	v_lshl_add_u64 v[2:3], s[100:101], 1, v[10:11]
	s_mov_b32 s13, s11
	s_lshl_b64 s[100:101], s[12:13], 15
	v_lshl_add_u64 v[10:11], s[100:101], 1, v[10:11]
	global_load_dwordx4 v[100:103], v[2:3], off
	global_load_dwordx4 v[104:107], v[10:11], off
.LBB0_1239:
	s_or_b64 exec, exec, s[8:9]
	v_add_u32_e32 v1, 0xa00, v6
	v_ashrrev_i32_e32 v2, 3, v1
	v_add_u32_e32 v1, s79, v2
	v_add_u32_e32 v1, 0xffffff80, v1
	v_cmp_gt_i32_e32 vcc, s64, v2
	v_cmp_lt_i32_e64 s[8:9], -1, v1
	s_and_b64 s[36:37], vcc, s[8:9]
	v_mov_b32_e32 v110, 0
	v_mov_b32_e32 v109, 0
	v_mov_b32_e32 v108, 0
	v_mov_b32_e32 v115, 0
	v_mov_b32_e32 v114, 0
	v_mov_b32_e32 v113, 0
	v_mov_b32_e32 v112, 0
	s_and_saveexec_b64 s[8:9], s[36:37]
	s_cbranch_execz .LBB0_1241
	v_mov_b64_e32 v[2:3], s[14:15]
	v_mad_u64_u32 v[0:1], s[14:15], v1, s1, v[2:3]
	v_mad_u64_u32 v[2:3], s[14:15], v0, s5, v[4:5]
	v_mov_b32_e32 v0, v3
	v_mad_u64_u32 v[0:1], s[14:15], v1, s5, v[0:1]
	v_mov_b32_e32 v3, v0
	s_lshl_b64 s[100:101], s[10:11], 15
	v_lshl_add_u64 v[0:1], s[100:101], 1, v[2:3]
	s_mov_b32 s13, s11
	s_lshl_b64 s[100:101], s[12:13], 15
	v_lshl_add_u64 v[2:3], s[100:101], 1, v[2:3]
	global_load_dwordx4 v[108:111], v[0:1], off
	global_load_dwordx4 v[112:115], v[2:3], off
	s_waitcnt vmcnt(1)
	v_mov_b32_e32 v0, v111

.LBB0_1243:
	v_readlane_b32 s8, v255, 16
	v_readlane_b32 s9, v255, 17
	v_and_b32_e32 v0, 63, v6
	s_and_b64 vcc, exec, s[8:9]
	s_cbranch_vccnz .LBB0_1289
	v_mov_b32_e32 v88, 0
	v_and_b32_e32 v2, 0x70, v8
	v_mov_b32_e32 v3, v88
	v_add_u32_e32 v1, 0, v2
	v_lshl_add_u64 v[136:137], s[42:43], 0, v[2:3]
	v_add_u32_e32 v2, 0x200, v6
	v_ashrrev_i32_e32 v177, 3, v2
	v_add_u32_e32 v2, 0x400, v6
	v_ashrrev_i32_e32 v179, 3, v2
	v_add_u32_e32 v2, 0x600, v6
	v_ashrrev_i32_e32 v181, 3, v2
	v_add_u32_e32 v2, 0x800, v6
	s_ashr_i32 s5, s35, 7
	v_ashrrev_i32_e32 v183, 3, v2
	v_add_u32_e32 v2, 0xa00, v6
	v_cmp_gt_u32_e64 s[8:9], 32, v0
	v_and_b32_e32 v0, 3, v6
	v_writelane_b32 v255, s5, 50
	s_lshl_b32 s5, s34, 5
	v_ashrrev_i32_e32 v185, 3, v2
	v_lshlrev_b32_e32 v4, 1, v6
	v_lshrrev_b32_e32 v2, 1, v6
	s_movk_i32 s71, 0x90
	v_lshlrev_b32_e32 v0, 3, v0
	v_writelane_b32 v255, s5, 52
	s_and_b32 s5, s5, 32
	v_lshlrev_b32_e32 v134, 3, v7
	v_and_b32_e32 v3, 19, v6
	v_and_b32_e32 v5, 8, v4
	v_and_b32_e32 v8, 4, v2
	v_lshrrev_b32_e32 v9, 2, v6
	v_lshlrev_b32_e32 v2, 2, v7
	v_mul_lo_u32 v7, v176, s71
	v_mul_lo_u32 v10, v177, s71
	v_mul_lo_u32 v11, v179, s71
	v_mul_lo_u32 v12, v181, s71
	v_mul_lo_u32 v13, v183, s71
	v_mul_lo_u32 v14, v185, s71
	v_and_or_b32 v138, v4, 32, v0
	s_mov_b32 s34, 0x41a00000
	s_mov_b32 s36, 2.0
	s_mov_b32 s60, 4.0
	s_mov_b32 s82, 0x40c00000
	s_mov_b32 s88, 0x41800000
	s_mov_b32 s92, 0x41900000
	s_mov_b32 s94, 0x41b00000
	v_mbcnt_lo_u32_b32 v0, -1, 0
	s_mov_b32 s15, 0
	v_writelane_b32 v255, s5, 53
	v_add_u32_e32 v133, 0xffffff80, v176
	v_add_u32_e32 v178, 0xffffff80, v177
	v_add_u32_e32 v180, 0xffffff80, v179
	v_add_u32_e32 v182, 0xffffff80, v181
	v_add_u32_e32 v184, 0xffffff80, v183
	v_add_u32_e32 v186, 0xffffff80, v185
	v_cndmask_b32_e64 v187, 0, 1.0, s[8:9]
	v_sub_u32_e32 v188, v139, v134
	v_and_or_b32 v189, v9, 3, v134
	v_or3_b32 v190, v3, v5, v8
	v_add_u32_e32 v191, v1, v7
	v_add_u32_e32 v192, v1, v10
	v_add_u32_e32 v193, v1, v11
	v_add_u32_e32 v194, v1, v12
	v_add_u32_e32 v195, v1, v13
	v_add_u32_e32 v196, v1, v14
	s_movk_i32 s72, 0x80
	s_mov_b32 s35, 0x41a80000
	s_mov_b32 s37, 0x40400000
	s_mov_b32 s61, 0x40a00000
	s_mov_b32 s83, 0x40e00000
	s_mov_b32 s89, 0x41880000
	s_mov_b32 s93, 0x41980000
	s_mov_b32 s95, 0x41b80000
	s_mov_b32 s73, 0xff800000
	v_lshlrev_b32_e32 v140, 1, v2
	v_mov_b32_e32 v197, 0x3fb8aa3b
	v_mov_b32_e32 v198, 0x42800000
	v_mbcnt_hi_u32_b32 v199, -1, v0
	v_mov_b32_e32 v200, 0xff800000
	s_mov_b32 s78, s2
	s_waitcnt vmcnt(0)
	s_branch .LBB0_1246

.LBB0_1264:
	s_ashr_i32 s41, s40, 31
	s_lshl_b64 s[46:47], s[40:41], 14
	s_or_b32 s46, s46, s85
	v_add_u32_e32 v2, s80, v139
	v_mov_b64_e32 v[0:1], s[46:47]
	v_mad_i64_i32 v[0:1], vcc, v2, s84, v[0:1]
	v_mov_b64_e32 v[2:3], s[42:43]
	v_mad_u64_u32 v[2:3], vcc, v0, s72, v[2:3]
	v_mov_b32_e32 v0, v3
	v_mad_u64_u32 v[0:1], vcc, v1, s72, v[0:1]
	v_mov_b32_e32 v3, v0
	s_ashr_i32 s11, s10, 31
	s_lshl_b64 s[100:101], s[10:11], 15
	v_lshl_add_u64 v[0:1], s[100:101], 1, v[2:3]
	v_lshlrev_b32_e32 v2, 1, v134
	v_mov_b32_e32 v3, v88
	v_lshl_add_u64 v[0:1], v[0:1], 0, v[2:3]
	global_load_dwordx4 v[116:119], v[0:1], off
	global_load_dwordx4 v[120:123], v[0:1], off offset:32
	global_load_dwordx4 v[124:127], v[0:1], off offset:64
	global_load_dwordx4 v[128:131], v[0:1], off offset:96
	v_add_u32_e32 v0, s70, v133
	v_mov_b32_e32 v89, v88
	v_cmp_gt_i32_e32 vcc, s64, v176
	v_cmp_lt_i32_e64 s[10:11], -1, v0
	v_mov_b32_e32 v90, v88
	v_mov_b32_e32 v91, v88
	v_mov_b64_e32 v[72:73], v[88:89]
	s_and_b64 vcc, vcc, s[10:11]
	v_mov_b32_e32 v64, 0
	v_mov_b64_e32 v[74:75], v[90:91]
	v_mov_b32_e32 v68, 0
	v_mov_b32_e32 v69, 0
	v_mov_b32_e32 v70, 0
	v_mov_b32_e32 v71, 0
	s_and_saveexec_b64 s[10:11], vcc
	s_cbranch_execz .LBB0_1266
	v_mov_b64_e32 v[2:3], s[46:47]
	v_mad_u64_u32 v[0:1], vcc, v0, s84, v[2:3]
	v_mad_u64_u32 v[2:3], vcc, v0, s72, v[136:137]
	v_mov_b32_e32 v0, v3
	v_mad_u64_u32 v[0:1], vcc, v1, s72, v[0:1]
	v_mov_b32_e32 v3, v0
	s_lshl_b64 s[100:101], s[14:15], 15
	v_lshl_add_u64 v[0:1], s[100:101], 1, v[2:3]
	s_mov_b32 s13, s15
	s_lshl_b64 s[100:101], s[12:13], 15
	v_lshl_add_u64 v[2:3], s[100:101], 1, v[2:3]
	global_load_dwordx4 v[68:71], v[0:1], off
	global_load_dwordx4 v[72:75], v[2:3], off
.LBB0_1266:
	s_or_b64 exec, exec, s[10:11]
	v_add_u32_e32 v0, s70, v178
	v_cmp_gt_i32_e32 vcc, s64, v177
	v_cmp_lt_i32_e64 s[10:11], -1, v0
	v_mov_b64_e32 v[76:77], v[88:89]
	s_and_b64 vcc, vcc, s[10:11]
	v_mov_b64_e32 v[78:79], v[90:91]
	v_mov_b32_e32 v65, 0
	v_mov_b32_e32 v66, 0
	v_mov_b32_e32 v67, 0
	s_and_saveexec_b64 s[10:11], vcc
	s_cbranch_execz .LBB0_1268
	v_mov_b64_e32 v[2:3], s[46:47]
	v_mad_u64_u32 v[0:1], vcc, v0, s84, v[2:3]
	v_mad_u64_u32 v[2:3], vcc, v0, s72, v[136:137]
	v_mov_b32_e32 v0, v3
	v_mad_u64_u32 v[0:1], vcc, v1, s72, v[0:1]
	v_mov_b32_e32 v3, v0
	s_lshl_b64 s[100:101], s[14:15], 15
	v_lshl_add_u64 v[0:1], s[100:101], 1, v[2:3]
	s_mov_b32 s13, s15
	s_lshl_b64 s[100:101], s[12:13], 15
	v_lshl_add_u64 v[2:3], s[100:101], 1, v[2:3]
	global_load_dwordx4 v[64:67], v[0:1], off
	global_load_dwordx4 v[76:79], v[2:3], off
.LBB0_1268:
	s_or_b64 exec, exec, s[10:11]
	v_add_u32_e32 v0, s70, v180
	v_mov_b32_e32 v89, v88
	v_cmp_gt_i32_e32 vcc, s64, v179
	v_cmp_lt_i32_e64 s[10:11], -1, v0
	v_mov_b32_e32 v90, v88
	v_mov_b32_e32 v91, v88
	v_mov_b64_e32 v[84:85], v[88:89]
	s_and_b64 vcc, vcc, s[10:11]
	v_mov_b32_e32 v92, 0
	v_mov_b64_e32 v[86:87], v[90:91]
	v_mov_b32_e32 v80, 0
	v_mov_b32_e32 v81, 0
	v_mov_b32_e32 v82, 0
	v_mov_b32_e32 v83, 0
	s_and_saveexec_b64 s[10:11], vcc
	s_cbranch_execz .LBB0_1270
	v_mov_b64_e32 v[2:3], s[46:47]
	v_mad_u64_u32 v[0:1], vcc, v0, s84, v[2:3]
	v_mad_u64_u32 v[2:3], vcc, v0, s72, v[136:137]
	v_mov_b32_e32 v0, v3
	v_mad_u64_u32 v[0:1], vcc, v1, s72, v[0:1]
	v_mov_b32_e32 v3, v0
	s_lshl_b64 s[100:101], s[14:15], 15
	v_lshl_add_u64 v[0:1], s[100:101], 1, v[2:3]
	s_mov_b32 s13, s15
	s_lshl_b64 s[100:101], s[12:13], 15
	v_lshl_add_u64 v[2:3], s[100:101], 1, v[2:3]
	global_load_dwordx4 v[80:83], v[0:1], off
	global_load_dwordx4 v[84:87], v[2:3], off
.LBB0_1270:
	s_or_b64 exec, exec, s[10:11]
	v_add_u32_e32 v0, s70, v182
	v_cmp_gt_i32_e32 vcc, s64, v181
	v_cmp_lt_i32_e64 s[10:11], -1, v0
	v_mov_b64_e32 v[98:99], v[90:91]
	s_and_b64 vcc, vcc, s[10:11]
	v_mov_b64_e32 v[96:97], v[88:89]
	v_mov_b32_e32 v93, 0
	v_mov_b32_e32 v94, 0
	v_mov_b32_e32 v95, 0
	s_and_saveexec_b64 s[10:11], vcc
	s_cbranch_execz .LBB0_1272
	v_mov_b64_e32 v[2:3], s[46:47]
	v_mad_u64_u32 v[0:1], vcc, v0, s84, v[2:3]
	v_mad_u64_u32 v[2:3], vcc, v0, s72, v[136:137]
	v_mov_b32_e32 v0, v3
	v_mad_u64_u32 v[0:1], vcc, v1, s72, v[0:1]
	v_mov_b32_e32 v3, v0
	s_lshl_b64 s[100:101], s[14:15], 15
	v_lshl_add_u64 v[0:1], s[100:101], 1, v[2:3]
	s_mov_b32 s13, s15
	s_lshl_b64 s[100:101], s[12:13], 15
	v_lshl_add_u64 v[2:3], s[100:101], 1, v[2:3]
	global_load_dwordx4 v[92:95], v[0:1], off
	global_load_dwordx4 v[96:99], v[2:3], off
.LBB0_1272:
	s_or_b64 exec, exec, s[10:11]
	v_add_u32_e32 v0, s70, v184
	v_mov_b32_e32 v90, v88
	v_mov_b32_e32 v91, v88
	v_cmp_gt_i32_e32 vcc, s64, v183
	v_cmp_lt_i32_e64 s[10:11], -1, v0
	v_mov_b32_e32 v89, v88
	v_mov_b64_e32 v[106:107], v[90:91]
	s_and_b64 vcc, vcc, s[10:11]
	v_mov_b32_e32 v111, 0
	v_mov_b64_e32 v[104:105], v[88:89]
	v_mov_b32_e32 v100, 0
	v_mov_b32_e32 v101, 0
	v_mov_b32_e32 v102, 0
	v_mov_b32_e32 v103, 0
	s_and_saveexec_b64 s[10:11], vcc
	s_cbranch_execz .LBB0_1274
	v_mov_b64_e32 v[2:3], s[46:47]
	v_mad_u64_u32 v[0:1], vcc, v0, s84, v[2:3]
	v_mad_u64_u32 v[2:3], vcc, v0, s72, v[136:137]
	v_mov_b32_e32 v0, v3
	v_mad_u64_u32 v[0:1], vcc, v1, s72, v[0:1]
	v_mov_b32_e32 v3, v0
	s_lshl_b64 s[100:101], s[14:15], 15
	v_lshl_add_u64 v[0:1], s[100:101], 1, v[2:3]
	s_mov_b32 s13, s15
	s_lshl_b64 s[100:101], s[12:13], 15
	v_lshl_add_u64 v[2:3], s[100:101], 1, v[2:3]
	global_load_dwordx4 v[100:103], v[0:1], off
	global_load_dwordx4 v[104:107], v[2:3], off
.LBB0_1274:
	s_or_b64 exec, exec, s[10:11]
	v_add_u32_e32 v0, s70, v186
	v_cmp_gt_i32_e32 vcc, s64, v185
	v_cmp_lt_i32_e64 s[10:11], -1, v0
	s_and_b64 vcc, vcc, s[10:11]
	v_mov_b32_e32 v110, 0
	v_mov_b32_e32 v109, 0
	v_mov_b32_e32 v108, 0
	v_mov_b32_e32 v115, 0
	v_mov_b32_e32 v114, 0
	v_mov_b32_e32 v113, 0
	v_mov_b32_e32 v112, 0
	s_and_saveexec_b64 s[10:11], vcc
	s_cbranch_execz .LBB0_1276
	v_mov_b64_e32 v[2:3], s[46:47]
	v_mad_u64_u32 v[0:1], s[46:47], v0, s84, v[2:3]
	v_mad_u64_u32 v[2:3], s[46:47], v0, s72, v[136:137]
	v_mov_b32_e32 v0, v3
	v_mad_u64_u32 v[0:1], s[46:47], v1, s72, v[0:1]
	v_mov_b32_e32 v3, v0
	s_lshl_b64 s[100:101], s[14:15], 15
	v_lshl_add_u64 v[0:1], s[100:101], 1, v[2:3]
	s_mov_b32 s13, s15
	s_lshl_b64 s[100:101], s[12:13], 15
	v_lshl_add_u64 v[2:3], s[100:101], 1, v[2:3]
	global_load_dwordx4 v[108:111], v[0:1], off
	global_load_dwordx4 v[112:115], v[2:3], off

.LBB0_2027:
	s_andn2_b64 vcc, exec, s[10:11]
	s_mov_b64 s[10:11], -1
	v_cvt_pk_bf16_f32 v0, v10, v12
	v_cvt_pk_bf16_f32 v1, v14, v17
	v_cvt_pk_bf16_f32 v2, v11, v13
	v_cvt_pk_bf16_f32 v3, v15, v16
	v_lshl_add_u64 v[234:235], v[8:9], 0, s[100:101]
	global_store_dwordx4 v[234:235], v[0:3], off
	s_mov_b32 s99, 1
	s_cbranch_vccnz .LBB0_1922
	s_andn2_b64 vcc, exec, s[4:5]
	s_cbranch_vccnz .LBB0_1921
	s_barrier
	s_branch .LBB0_1921

.LBB0_2088:
	v_readlane_b32 s14, v255, 16
	v_bfe_u32 v7, v6, 5, 1
	v_readlane_b32 s15, v255, 17
	v_and_b32_e32 v139, 31, v6
	s_and_b64 vcc, exec, s[14:15]
	v_lshlrev_b32_e32 v132, 4, v7
	v_lshlrev_b32_e32 v8, 4, v6
	v_ashrrev_i32_e32 v176, 3, v6
	s_cbranch_vccnz .LBB0_2102
	s_ashr_i32 s5, s4, 31
	s_lshl_b64 s[14:15], s[4:5], 14
	s_or_b32 s14, s14, s65
	v_add_u32_e32 v2, s7, v139
	v_mov_b64_e32 v[0:1], s[14:15]
	v_mad_i64_i32 v[0:1], s[36:37], v2, s1, v[0:1]
	s_movk_i32 s5, 0x80
	v_mov_b64_e32 v[2:3], s[42:43]
	v_mad_u64_u32 v[2:3], s[36:37], v0, s5, v[2:3]
	v_mov_b32_e32 v0, v3
	v_mad_u64_u32 v[0:1], s[36:37], v1, s5, v[0:1]
	v_mov_b32_e32 v3, v0
	s_ashr_i32 s11, s10, 31
	v_mov_b32_e32 v64, 0
	s_lshl_b64 s[100:101], s[10:11], 15
	v_lshl_add_u64 v[0:1], s[100:101], 1, v[2:3]
	v_mov_b32_e32 v133, v64
	v_lshl_add_u64 v[0:1], v[0:1], 0, v[132:133]
	global_load_dwordx4 v[48:51], v[0:1], off
	global_load_dwordx4 v[52:55], v[0:1], off offset:32
	global_load_dwordx4 v[56:59], v[0:1], off offset:64
	global_load_dwordx4 v[60:63], v[0:1], off offset:96
	v_and_b32_e32 v0, 0x70, v8
	v_mov_b32_e32 v1, v64
	v_lshl_add_u64 v[4:5], s[42:43], 0, v[0:1]
	v_add_u32_e32 v0, s93, v176
	v_add_u32_e32 v0, 0xffffff80, v0
	v_mov_b32_e32 v76, 0
	v_mov_b32_e32 v77, v64
	v_cmp_gt_i32_e32 vcc, s64, v176
	v_cmp_lt_i32_e64 s[10:11], -1, v0
	v_mov_b32_e32 v78, v64
	v_mov_b32_e32 v79, v64
	v_mov_b64_e32 v[72:73], v[76:77]
	s_and_b64 s[36:37], vcc, s[10:11]
	s_mov_b32 s9, 0
	v_mov_b64_e32 v[74:75], v[78:79]
	v_mov_b32_e32 v68, 0
	v_mov_b32_e32 v69, 0
	v_mov_b32_e32 v70, 0
	v_mov_b32_e32 v71, 0
	s_and_saveexec_b64 s[10:11], s[36:37]
	s_cbranch_execz .LBB0_2091
	v_mov_b64_e32 v[2:3], s[14:15]
	v_mad_u64_u32 v[0:1], s[36:37], v0, s1, v[2:3]
	v_mad_u64_u32 v[2:3], s[36:37], v0, s5, v[4:5]
	v_mov_b32_e32 v0, v3
	v_mad_u64_u32 v[0:1], s[36:37], v1, s5, v[0:1]
	v_mov_b32_e32 v3, v0
	s_lshl_b64 s[100:101], s[8:9], 15
	v_lshl_add_u64 v[0:1], s[100:101], 1, v[2:3]
	s_mov_b32 s13, s9
	s_lshl_b64 s[100:101], s[12:13], 15
	v_lshl_add_u64 v[2:3], s[100:101], 1, v[2:3]
	global_load_dwordx4 v[68:71], v[0:1], off
	global_load_dwordx4 v[72:75], v[2:3], off
.LBB0_2091:
	s_or_b64 exec, exec, s[10:11]
	v_add_u32_e32 v0, 0x200, v6
	v_ashrrev_i32_e32 v1, 3, v0
	v_add_u32_e32 v0, s93, v1
	v_add_u32_e32 v0, 0xffffff80, v0
	v_cmp_gt_i32_e32 vcc, s64, v1
	v_cmp_lt_i32_e64 s[10:11], -1, v0
	s_and_b64 s[36:37], vcc, s[10:11]
	v_mov_b32_e32 v65, 0
	v_mov_b32_e32 v66, 0
	v_mov_b32_e32 v67, 0
	s_and_saveexec_b64 s[10:11], s[36:37]
	s_cbranch_execz .LBB0_2093
	v_mov_b64_e32 v[2:3], s[14:15]
	v_mad_u64_u32 v[0:1], s[36:37], v0, s1, v[2:3]
	v_mad_u64_u32 v[2:3], s[36:37], v0, s5, v[4:5]
	v_mov_b32_e32 v0, v3
	v_mad_u64_u32 v[0:1], s[36:37], v1, s5, v[0:1]
	v_mov_b32_e32 v3, v0
	s_lshl_b64 s[100:101], s[8:9], 15
	v_lshl_add_u64 v[0:1], s[100:101], 1, v[2:3]
	s_mov_b32 s13, s9
	s_lshl_b64 s[100:101], s[12:13], 15
	v_lshl_add_u64 v[2:3], s[100:101], 1, v[2:3]
	global_load_dwordx4 v[64:67], v[0:1], off
	global_load_dwordx4 v[76:79], v[2:3], off
.LBB0_2093:
	s_or_b64 exec, exec, s[10:11]
	v_add_u32_e32 v0, 0x400, v6
	v_ashrrev_i32_e32 v1, 3, v0
	v_add_u32_e32 v0, s93, v1
	v_mov_b32_e32 v96, 0
	v_add_u32_e32 v0, 0xffffff80, v0
	v_mov_b32_e32 v97, v96
	v_cmp_gt_i32_e32 vcc, s64, v1
	v_cmp_lt_i32_e64 s[10:11], -1, v0
	v_mov_b32_e32 v98, v96
	v_mov_b32_e32 v99, v96
	v_mov_b64_e32 v[84:85], v[96:97]
	s_and_b64 s[36:37], vcc, s[10:11]
	v_mov_b64_e32 v[86:87], v[98:99]
	v_mov_b32_e32 v80, v96
	v_mov_b32_e32 v81, v96
	v_mov_b32_e32 v82, v96
	v_mov_b32_e32 v83, v96
	s_and_saveexec_b64 s[10:11], s[36:37]
	s_cbranch_execz .LBB0_2095
	v_mov_b64_e32 v[2:3], s[14:15]
	v_mad_u64_u32 v[0:1], s[36:37], v0, s1, v[2:3]
	v_mad_u64_u32 v[2:3], s[36:37], v0, s5, v[4:5]
	v_mov_b32_e32 v0, v3
	v_mad_u64_u32 v[0:1], s[36:37], v1, s5, v[0:1]
	v_mov_b32_e32 v3, v0
	s_lshl_b64 s[100:101], s[8:9], 15
	v_lshl_add_u64 v[0:1], s[100:101], 1, v[2:3]
	s_mov_b32 s13, s9
	s_lshl_b64 s[100:101], s[12:13], 15
	v_lshl_add_u64 v[2:3], s[100:101], 1, v[2:3]
	global_load_dwordx4 v[80:83], v[0:1], off
	global_load_dwordx4 v[84:87], v[2:3], off
.LBB0_2095:
	s_or_b64 exec, exec, s[10:11]
	v_add_u32_e32 v0, 0x600, v6
	v_ashrrev_i32_e32 v1, 3, v0
	v_add_u32_e32 v0, s93, v1
	v_add_u32_e32 v0, 0xffffff80, v0
	v_cmp_gt_i32_e32 vcc, s64, v1
	v_cmp_lt_i32_e64 s[10:11], -1, v0
	s_and_b64 s[36:37], vcc, s[10:11]
	v_mov_b32_e32 v92, v96
	v_mov_b32_e32 v93, v96
	v_mov_b32_e32 v94, v96
	v_mov_b32_e32 v95, v96
	s_and_saveexec_b64 s[10:11], s[36:37]
	s_cbranch_execz .LBB0_2097
	v_mov_b64_e32 v[2:3], s[14:15]
	v_mad_u64_u32 v[0:1], s[36:37], v0, s1, v[2:3]
	v_mad_u64_u32 v[2:3], s[36:37], v0, s5, v[4:5]
	v_mov_b32_e32 v0, v3
	v_mad_u64_u32 v[0:1], s[36:37], v1, s5, v[0:1]
	v_mov_b32_e32 v3, v0
	s_lshl_b64 s[100:101], s[8:9], 15
	v_lshl_add_u64 v[0:1], s[100:101], 1, v[2:3]
	s_mov_b32 s13, s9
	s_lshl_b64 s[100:101], s[12:13], 15
	v_lshl_add_u64 v[2:3], s[100:101], 1, v[2:3]
	global_load_dwordx4 v[92:95], v[0:1], off
	global_load_dwordx4 v[96:99], v[2:3], off
.LBB0_2097:
	s_or_b64 exec, exec, s[10:11]
	v_add_u32_e32 v0, 0x800, v6
	v_ashrrev_i32_e32 v0, 3, v0
	v_add_u32_e32 v1, s93, v0
	v_cmp_gt_i32_e32 vcc, s64, v0
	v_mov_b32_e32 v0, 0
	v_add_u32_e32 v9, 0xffffff80, v1
	v_mov_b32_e32 v2, v0
	v_mov_b32_e32 v3, v0
	v_cmp_lt_i32_e64 s[10:11], -1, v9
	v_mov_b32_e32 v1, v0
	v_mov_b64_e32 v[106:107], v[2:3]
	s_and_b64 s[36:37], vcc, s[10:11]
	v_mov_b64_e32 v[104:105], v[0:1]
	v_mov_b32_e32 v100, 0
	v_mov_b32_e32 v101, 0
	v_mov_b32_e32 v102, 0
	v_mov_b32_e32 v103, 0
	s_and_saveexec_b64 s[10:11], s[36:37]
	s_cbranch_execz .LBB0_2099
	v_mov_b64_e32 v[2:3], s[14:15]
	v_mad_u64_u32 v[2:3], s[36:37], v9, s1, v[2:3]
	v_mad_u64_u32 v[10:11], s[36:37], v2, s5, v[4:5]
	v_mov_b32_e32 v2, v11
	v_mad_u64_u32 v[2:3], s[36:37], v3, s5, v[2:3]
	v_mov_b32_e32 v11, v2
	s_lshl_b64 s[100:101], s[8:9], 15
	v_lshl_add_u64 v[2:3], s[100:101], 1, v[10:11]
	s_mov_b32 s13, s9
	s_lshl_b64 s[100:101], s[12:13], 15
	v_lshl_add_u64 v[10:11], s[100:101], 1, v[10:11]
	global_load_dwordx4 v[100:103], v[2:3], off
	global_load_dwordx4 v[104:107], v[10:11], off
.LBB0_2099:
	s_or_b64 exec, exec, s[10:11]
	v_add_u32_e32 v1, 0xa00, v6
	v_ashrrev_i32_e32 v2, 3, v1
	v_add_u32_e32 v1, s93, v2
	v_add_u32_e32 v1, 0xffffff80, v1
	v_cmp_gt_i32_e32 vcc, s64, v2
	v_cmp_lt_i32_e64 s[10:11], -1, v1
	s_and_b64 s[36:37], vcc, s[10:11]
	v_mov_b32_e32 v110, 0
	v_mov_b32_e32 v109, 0
	v_mov_b32_e32 v108, 0
	v_mov_b32_e32 v115, 0
	v_mov_b32_e32 v114, 0
	v_mov_b32_e32 v113, 0
	v_mov_b32_e32 v112, 0
	s_and_saveexec_b64 s[10:11], s[36:37]
	s_cbranch_execz .LBB0_2101
	v_mov_b64_e32 v[2:3], s[14:15]
	v_mad_u64_u32 v[0:1], s[14:15], v1, s1, v[2:3]
	v_mad_u64_u32 v[2:3], s[14:15], v0, s5, v[4:5]
	v_mov_b32_e32 v0, v3
	v_mad_u64_u32 v[0:1], s[14:15], v1, s5, v[0:1]
	v_mov_b32_e32 v3, v0
	s_lshl_b64 s[100:101], s[8:9], 15
	v_lshl_add_u64 v[0:1], s[100:101], 1, v[2:3]
	s_mov_b32 s13, s9
	s_lshl_b64 s[100:101], s[12:13], 15
	v_lshl_add_u64 v[2:3], s[100:101], 1, v[2:3]
	global_load_dwordx4 v[108:111], v[0:1], off
	global_load_dwordx4 v[112:115], v[2:3], off
	s_waitcnt vmcnt(1)
	v_mov_b32_e32 v0, v111

.LBB0_2103:
	v_readlane_b32 s8, v255, 16
	v_readlane_b32 s9, v255, 17
	v_and_b32_e32 v0, 63, v6
	s_and_b64 vcc, exec, s[8:9]
	s_cbranch_vccnz .LBB0_2150
	v_mov_b32_e32 v88, 0
	v_and_b32_e32 v2, 0x70, v8
	v_mov_b32_e32 v3, v88
	v_add_u32_e32 v1, 0, v2
	v_lshl_add_u64 v[136:137], s[42:43], 0, v[2:3]
	v_add_u32_e32 v2, 0x200, v6
	v_ashrrev_i32_e32 v177, 3, v2
	v_add_u32_e32 v2, 0x400, v6
	v_ashrrev_i32_e32 v179, 3, v2
	v_add_u32_e32 v2, 0x600, v6
	v_ashrrev_i32_e32 v181, 3, v2
	v_add_u32_e32 v2, 0x800, v6
	v_ashrrev_i32_e32 v183, 3, v2
	v_add_u32_e32 v2, 0xa00, v6
	v_cmp_gt_u32_e64 s[10:11], 32, v0
	v_and_b32_e32 v0, 3, v6
	s_ashr_i32 s5, s35, 7
	s_lshl_b32 s69, s34, 5
	v_ashrrev_i32_e32 v185, 3, v2
	v_lshlrev_b32_e32 v4, 1, v6
	v_lshrrev_b32_e32 v2, 1, v6
	s_movk_i32 s71, 0x90
	v_lshlrev_b32_e32 v0, 3, v0
	v_writelane_b32 v255, s5, 52
	s_and_b32 s5, s69, 32
	v_lshlrev_b32_e32 v134, 3, v7
	v_and_b32_e32 v3, 19, v6
	v_and_b32_e32 v5, 8, v4
	v_and_b32_e32 v8, 4, v2
	v_lshrrev_b32_e32 v9, 2, v6
	v_lshlrev_b32_e32 v2, 2, v7
	v_mul_lo_u32 v7, v176, s71
	v_mul_lo_u32 v10, v177, s71
	v_mul_lo_u32 v11, v179, s71
	v_mul_lo_u32 v12, v181, s71
	v_mul_lo_u32 v13, v183, s71
	v_mul_lo_u32 v14, v185, s71
	v_and_or_b32 v138, v4, 32, v0
	s_mov_b32 s34, 0x41a00000
	s_mov_b32 s36, 2.0
	s_mov_b32 s60, 4.0
	s_mov_b32 s82, 0x40c00000
	s_mov_b32 s88, 0x41800000
	s_mov_b32 s94, 0x41900000
	s_mov_b32 s96, 0x41b00000
	v_mbcnt_lo_u32_b32 v0, -1, 0
	s_mov_b32 s9, 0
	v_writelane_b32 v255, s5, 53
	v_add_u32_e32 v133, 0xffffff80, v176
	v_add_u32_e32 v178, 0xffffff80, v177
	v_add_u32_e32 v180, 0xffffff80, v179
	v_add_u32_e32 v182, 0xffffff80, v181
	v_add_u32_e32 v184, 0xffffff80, v183
	v_add_u32_e32 v186, 0xffffff80, v185
	v_cndmask_b32_e64 v187, 0, 1.0, s[10:11]
	v_sub_u32_e32 v188, v139, v134
	v_and_or_b32 v189, v9, 3, v134
	v_or3_b32 v190, v3, v5, v8
	v_add_u32_e32 v191, v1, v7
	v_add_u32_e32 v192, v1, v10
	v_add_u32_e32 v193, v1, v11
	v_add_u32_e32 v194, v1, v12
	v_add_u32_e32 v195, v1, v13
	v_add_u32_e32 v196, v1, v14
	s_movk_i32 s72, 0x80
	s_mov_b32 s35, 0x41a80000
	s_mov_b32 s37, 0x40400000
	s_mov_b32 s61, 0x40a00000
	s_mov_b32 s83, 0x40e00000
	s_mov_b32 s89, 0x41880000
	s_mov_b32 s95, 0x41980000
	s_mov_b32 s97, 0x41b80000
	s_mov_b32 s73, 0xff800000
	v_lshlrev_b32_e32 v140, 1, v2
	v_mov_b32_e32 v197, 0x3fb8aa3b
	v_mov_b32_e32 v198, 0x42800000
	v_mbcnt_hi_u32_b32 v199, -1, v0
	v_mov_b32_e32 v200, 0xff800000
	s_mov_b32 s78, s2
	s_waitcnt vmcnt(0)
	s_branch .LBB0_2106

.LBB0_2124:
	s_ashr_i32 s75, s74, 31
	s_lshl_b64 s[46:47], s[74:75], 14
	s_or_b32 s46, s46, s85
	v_add_u32_e32 v2, s80, v139
	v_mov_b64_e32 v[0:1], s[46:47]
	v_mad_i64_i32 v[0:1], vcc, v2, s84, v[0:1]
	v_mov_b64_e32 v[2:3], s[42:43]
	v_mad_u64_u32 v[2:3], vcc, v0, s72, v[2:3]
	v_mov_b32_e32 v0, v3
	v_mad_u64_u32 v[0:1], vcc, v1, s72, v[0:1]
	v_mov_b32_e32 v3, v0
	s_ashr_i32 s13, s12, 31
	s_lshl_b64 s[100:101], s[12:13], 15
	v_lshl_add_u64 v[0:1], s[100:101], 1, v[2:3]
	v_lshlrev_b32_e32 v2, 1, v134
	v_mov_b32_e32 v3, v88
	v_lshl_add_u64 v[0:1], v[0:1], 0, v[2:3]
	global_load_dwordx4 v[116:119], v[0:1], off
	global_load_dwordx4 v[120:123], v[0:1], off offset:32
	global_load_dwordx4 v[124:127], v[0:1], off offset:64
	global_load_dwordx4 v[128:131], v[0:1], off offset:96
	v_add_u32_e32 v0, s79, v133
	v_mov_b32_e32 v89, v88
	v_cmp_gt_i32_e32 vcc, s64, v176
	v_cmp_lt_i32_e64 s[12:13], -1, v0
	v_mov_b32_e32 v90, v88
	v_mov_b32_e32 v91, v88
	v_mov_b64_e32 v[72:73], v[88:89]
	s_and_b64 vcc, vcc, s[12:13]
	v_mov_b32_e32 v64, 0
	v_mov_b64_e32 v[74:75], v[90:91]
	v_mov_b32_e32 v68, 0
	v_mov_b32_e32 v69, 0
	v_mov_b32_e32 v70, 0
	v_mov_b32_e32 v71, 0
	s_and_saveexec_b64 s[12:13], vcc
	s_cbranch_execz .LBB0_2126
	v_mov_b64_e32 v[2:3], s[46:47]
	v_mad_u64_u32 v[0:1], vcc, v0, s84, v[2:3]
	v_mad_u64_u32 v[2:3], vcc, v0, s72, v[136:137]
	v_mov_b32_e32 v0, v3
	v_mad_u64_u32 v[0:1], vcc, v1, s72, v[0:1]
	v_mov_b32_e32 v3, v0
	s_lshl_b64 s[100:101], s[8:9], 15
	v_lshl_add_u64 v[0:1], s[100:101], 1, v[2:3]
	s_mov_b32 s15, s9
	s_lshl_b64 s[100:101], s[14:15], 15
	v_lshl_add_u64 v[2:3], s[100:101], 1, v[2:3]
	global_load_dwordx4 v[68:71], v[0:1], off
	global_load_dwordx4 v[72:75], v[2:3], off
.LBB0_2126:
	s_or_b64 exec, exec, s[12:13]
	v_add_u32_e32 v0, s79, v178
	v_cmp_gt_i32_e32 vcc, s64, v177
	v_cmp_lt_i32_e64 s[12:13], -1, v0
	v_mov_b64_e32 v[76:77], v[88:89]
	s_and_b64 vcc, vcc, s[12:13]
	v_mov_b64_e32 v[78:79], v[90:91]
	v_mov_b32_e32 v65, 0
	v_mov_b32_e32 v66, 0
	v_mov_b32_e32 v67, 0
	s_and_saveexec_b64 s[12:13], vcc
	s_cbranch_execz .LBB0_2128
	v_mov_b64_e32 v[2:3], s[46:47]
	v_mad_u64_u32 v[0:1], vcc, v0, s84, v[2:3]
	v_mad_u64_u32 v[2:3], vcc, v0, s72, v[136:137]
	v_mov_b32_e32 v0, v3
	v_mad_u64_u32 v[0:1], vcc, v1, s72, v[0:1]
	v_mov_b32_e32 v3, v0
	s_lshl_b64 s[100:101], s[8:9], 15
	v_lshl_add_u64 v[0:1], s[100:101], 1, v[2:3]
	s_mov_b32 s15, s9
	s_lshl_b64 s[100:101], s[14:15], 15
	v_lshl_add_u64 v[2:3], s[100:101], 1, v[2:3]
	global_load_dwordx4 v[64:67], v[0:1], off
	global_load_dwordx4 v[76:79], v[2:3], off
.LBB0_2128:
	s_or_b64 exec, exec, s[12:13]
	v_add_u32_e32 v0, s79, v180
	v_mov_b32_e32 v89, v88
	v_cmp_gt_i32_e32 vcc, s64, v179
	v_cmp_lt_i32_e64 s[12:13], -1, v0
	v_mov_b32_e32 v90, v88
	v_mov_b32_e32 v91, v88
	v_mov_b64_e32 v[84:85], v[88:89]
	s_and_b64 vcc, vcc, s[12:13]
	v_mov_b32_e32 v92, 0
	v_mov_b64_e32 v[86:87], v[90:91]
	v_mov_b32_e32 v80, 0
	v_mov_b32_e32 v81, 0
	v_mov_b32_e32 v82, 0
	v_mov_b32_e32 v83, 0
	s_and_saveexec_b64 s[12:13], vcc
	s_cbranch_execz .LBB0_2130
	v_mov_b64_e32 v[2:3], s[46:47]
	v_mad_u64_u32 v[0:1], vcc, v0, s84, v[2:3]
	v_mad_u64_u32 v[2:3], vcc, v0, s72, v[136:137]
	v_mov_b32_e32 v0, v3
	v_mad_u64_u32 v[0:1], vcc, v1, s72, v[0:1]
	v_mov_b32_e32 v3, v0
	s_lshl_b64 s[100:101], s[8:9], 15
	v_lshl_add_u64 v[0:1], s[100:101], 1, v[2:3]
	s_mov_b32 s15, s9
	s_lshl_b64 s[100:101], s[14:15], 15
	v_lshl_add_u64 v[2:3], s[100:101], 1, v[2:3]
	global_load_dwordx4 v[80:83], v[0:1], off
	global_load_dwordx4 v[84:87], v[2:3], off
.LBB0_2130:
	s_or_b64 exec, exec, s[12:13]
	v_add_u32_e32 v0, s79, v182
	v_cmp_gt_i32_e32 vcc, s64, v181
	v_cmp_lt_i32_e64 s[12:13], -1, v0
	v_mov_b64_e32 v[98:99], v[90:91]
	s_and_b64 vcc, vcc, s[12:13]
	v_mov_b64_e32 v[96:97], v[88:89]
	v_mov_b32_e32 v93, 0
	v_mov_b32_e32 v94, 0
	v_mov_b32_e32 v95, 0
	s_and_saveexec_b64 s[12:13], vcc
	s_cbranch_execz .LBB0_2132
	v_mov_b64_e32 v[2:3], s[46:47]
	v_mad_u64_u32 v[0:1], vcc, v0, s84, v[2:3]
	v_mad_u64_u32 v[2:3], vcc, v0, s72, v[136:137]
	v_mov_b32_e32 v0, v3
	v_mad_u64_u32 v[0:1], vcc, v1, s72, v[0:1]
	v_mov_b32_e32 v3, v0
	s_lshl_b64 s[100:101], s[8:9], 15
	v_lshl_add_u64 v[0:1], s[100:101], 1, v[2:3]
	s_mov_b32 s15, s9
	s_lshl_b64 s[100:101], s[14:15], 15
	v_lshl_add_u64 v[2:3], s[100:101], 1, v[2:3]
	global_load_dwordx4 v[92:95], v[0:1], off
	global_load_dwordx4 v[96:99], v[2:3], off
.LBB0_2132:
	s_or_b64 exec, exec, s[12:13]
	v_add_u32_e32 v0, s79, v184
	v_mov_b32_e32 v90, v88
	v_mov_b32_e32 v91, v88
	v_cmp_gt_i32_e32 vcc, s64, v183
	v_cmp_lt_i32_e64 s[12:13], -1, v0
	v_mov_b32_e32 v89, v88
	v_mov_b64_e32 v[106:107], v[90:91]
	s_and_b64 vcc, vcc, s[12:13]
	v_mov_b32_e32 v111, 0
	v_mov_b64_e32 v[104:105], v[88:89]
	v_mov_b32_e32 v100, 0
	v_mov_b32_e32 v101, 0
	v_mov_b32_e32 v102, 0
	v_mov_b32_e32 v103, 0
	s_and_saveexec_b64 s[12:13], vcc
	s_cbranch_execz .LBB0_2134
	v_mov_b64_e32 v[2:3], s[46:47]
	v_mad_u64_u32 v[0:1], vcc, v0, s84, v[2:3]
	v_mad_u64_u32 v[2:3], vcc, v0, s72, v[136:137]
	v_mov_b32_e32 v0, v3
	v_mad_u64_u32 v[0:1], vcc, v1, s72, v[0:1]
	v_mov_b32_e32 v3, v0
	s_lshl_b64 s[100:101], s[8:9], 15
	v_lshl_add_u64 v[0:1], s[100:101], 1, v[2:3]
	s_mov_b32 s15, s9
	s_lshl_b64 s[100:101], s[14:15], 15
	v_lshl_add_u64 v[2:3], s[100:101], 1, v[2:3]
	global_load_dwordx4 v[100:103], v[0:1], off
	global_load_dwordx4 v[104:107], v[2:3], off
.LBB0_2134:
	s_or_b64 exec, exec, s[12:13]
	v_add_u32_e32 v0, s79, v186
	v_cmp_gt_i32_e32 vcc, s64, v185
	v_cmp_lt_i32_e64 s[12:13], -1, v0
	s_and_b64 vcc, vcc, s[12:13]
	v_mov_b32_e32 v110, 0
	v_mov_b32_e32 v109, 0
	v_mov_b32_e32 v108, 0
	v_mov_b32_e32 v115, 0
	v_mov_b32_e32 v114, 0
	v_mov_b32_e32 v113, 0
	v_mov_b32_e32 v112, 0
	s_and_saveexec_b64 s[12:13], vcc
	s_cbranch_execz .LBB0_2136
	v_mov_b64_e32 v[2:3], s[46:47]
	v_mad_u64_u32 v[0:1], s[46:47], v0, s84, v[2:3]
	v_mad_u64_u32 v[2:3], s[46:47], v0, s72, v[136:137]
	v_mov_b32_e32 v0, v3
	v_mad_u64_u32 v[0:1], s[46:47], v1, s72, v[0:1]
	v_mov_b32_e32 v3, v0
	s_lshl_b64 s[100:101], s[8:9], 15
	v_lshl_add_u64 v[0:1], s[100:101], 1, v[2:3]
	s_mov_b32 s15, s9
	s_lshl_b64 s[100:101], s[14:15], 15
	v_lshl_add_u64 v[2:3], s[100:101], 1, v[2:3]
	global_load_dwordx4 v[108:111], v[0:1], off
	global_load_dwordx4 v[112:115], v[2:3], off

.LBB0_2801:
	s_lshr_b32 s98, s69, 6
	s_lshl_b32 s98, s98, 21
	s_bfe_u32 s100, s69, 0x10005
	s_lshl_b32 s100, s100, 5
	s_or_b32 s98, s98, s100
	s_add_i32 s0, s48, 0xfffff400
	s_lshl_b64 s[46:47], s[0:1], 1
	s_add_u32 s0, s56, s46
	s_addc_u32 s25, s57, s47
	s_ashr_i32 s49, s48, 31
	s_lshl_b64 s[46:47], s[48:49], 16
	s_add_u32 s37, s42, s46
	s_addc_u32 s46, s43, s47
	s_cmp_lt_i32 s40, 12
	s_cselect_b32 s98, s98, s69
	s_movk_i32 s100, 0x100
	s_cselect_b32 s100, 0x800000, s100
	s_mov_b32 s101, 0
	s_cselect_b32 s0, s37, s0
	v_lshl_add_u32 v164, v198, 3, s98
	s_cselect_b32 s25, s46, s25
	v_mov_b32_e32 v166, s0
	s_movk_i32 s0, 0x40
	v_mov_b32_e32 v167, s25
	s_cselect_b32 s0, s0, 0x800
	v_ashrrev_i32_e32 v165, 31, v164
	v_lshl_add_u32 v198, s36, 8, v199
	v_cvt_pk_bf16_f32 v212, v200, v202
	v_cvt_pk_bf16_f32 v213, v204, v207
	v_cvt_pk_bf16_f32 v214, v201, v203
	v_mov_b32_e32 v170, v173
	v_mov_b32_e32 v171, v173
	v_mov_b32_e32 v200, v173
	v_mov_b32_e32 v201, v173
	v_lshl_add_u64 v[164:165], v[164:165], 1, v[166:167]
	v_mad_i64_i32 v[166:167], s[36:37], s0, v198, 0
	v_cvt_pk_bf16_f32 v215, v205, v206
	v_mov_b32_e32 v168, v172
	v_mov_b32_e32 v169, v172
	v_pk_fma_f32 v[202:203], v[42:43], v[200:201], v[58:59]
	v_pk_fma_f32 v[204:205], v[40:41], v[170:171], v[56:57]
	v_mov_b32_e32 v173, v172
	v_pk_fma_f32 v[200:201], v[34:35], v[200:201], v[46:47]
	v_pk_fma_f32 v[170:171], v[32:33], v[170:171], v[44:45]
	v_lshl_add_u64 v[166:167], v[166:167], 1, v[164:165]
	v_pk_fma_f32 v[162:163], v[162:163], v[172:173], v[202:203]
	v_pk_fma_f32 v[160:161], v[160:161], v[168:169], v[204:205]
	v_pk_fma_f32 v[158:159], v[158:159], v[172:173], v[200:201]
	v_pk_fma_f32 v[156:157], v[156:157], v[168:169], v[170:171]
	s_cmp_gt_i32 s23, 1
	s_mov_b64 s[36:37], -1
	global_store_dwordx4 v[166:167], v[212:215], off
	s_cbranch_scc0 .LBB0_2803
	v_mul_f32_e32 v199, 0xbfb8aa3b, v163
	v_mul_f32_e32 v168, 0xbfb8aa3b, v160
	v_mul_f32_e32 v169, 0xbfb8aa3b, v156
	v_mul_f32_e32 v170, 0xbfb8aa3b, v161
	v_mul_f32_e32 v171, 0xbfb8aa3b, v157
	v_mul_f32_e32 v172, 0xbfb8aa3b, v162
	v_mul_f32_e32 v173, 0xbfb8aa3b, v158
	v_exp_f32_e32 v199, v199
	v_mul_f32_e32 v200, 0xbfb8aa3b, v159
	v_exp_f32_e32 v168, v168
	v_exp_f32_e32 v169, v169
	v_exp_f32_e32 v170, v170
	v_exp_f32_e32 v171, v171
	v_exp_f32_e32 v172, v172
	v_exp_f32_e32 v173, v173
	v_exp_f32_e32 v201, v200
	v_add_f32_e32 v199, 1.0, v199
	v_add_f32_e32 v168, 1.0, v168
	v_add_f32_e32 v169, 1.0, v169
	v_add_f32_e32 v170, 1.0, v170
	v_add_f32_e32 v171, 1.0, v171
	v_add_f32_e32 v172, 1.0, v172
	v_add_f32_e32 v173, 1.0, v173
	v_rcp_f32_e32 v200, v199
	v_add_f32_e32 v199, 1.0, v201
	v_rcp_f32_e32 v168, v168
	v_rcp_f32_e32 v169, v169
	v_rcp_f32_e32 v170, v170
	v_rcp_f32_e32 v171, v171
	v_rcp_f32_e32 v172, v172
	v_rcp_f32_e32 v173, v173
	v_rcp_f32_e32 v199, v199
	s_mov_b64 s[36:37], 0

.LBB0_2807:
	v_cvt_pk_bf16_f32 v156, v168, v170
	v_cvt_pk_bf16_f32 v157, v172, v200
	v_cvt_pk_bf16_f32 v158, v169, v171
	v_cvt_pk_bf16_f32 v159, v173, v199
	v_lshl_add_u64 v[234:235], v[166:167], 0, s[100:101]
	global_store_dwordx4 v[234:235], v[156:159], off
	s_cmp_gt_i32 s23, 1
	s_mov_b64 s[36:37], -1
	v_pk_fma_f32 v[156:157], v[68:69], v[174:175], v[72:73] op_sel:[0,1,0]
	v_pk_fma_f32 v[158:159], v[70:71], v[174:175], v[74:75] op_sel:[0,1,0]
	v_pk_fma_f32 v[152:153], v[152:153], v[174:175], v[156:157] op_sel_hi:[1,0,1]
	v_pk_fma_f32 v[154:155], v[154:155], v[174:175], v[158:159] op_sel_hi:[1,0,1]
	v_pk_fma_f32 v[156:157], v[60:61], v[174:175], v[64:65] op_sel:[0,1,0]
	v_pk_fma_f32 v[158:159], v[62:63], v[174:175], v[66:67] op_sel:[0,1,0]
	v_pk_fma_f32 v[148:149], v[148:149], v[174:175], v[156:157] op_sel_hi:[1,0,1]
	v_pk_fma_f32 v[150:151], v[150:151], v[174:175], v[158:159] op_sel_hi:[1,0,1]
	s_cbranch_scc0 .LBB0_2809
	v_mul_f32_e32 v162, 0xbfb8aa3b, v155
	v_mul_f32_e32 v156, 0xbfb8aa3b, v152
	v_mul_f32_e32 v157, 0xbfb8aa3b, v148
	v_mul_f32_e32 v158, 0xbfb8aa3b, v153
	v_mul_f32_e32 v159, 0xbfb8aa3b, v149
	v_mul_f32_e32 v160, 0xbfb8aa3b, v154
	v_mul_f32_e32 v161, 0xbfb8aa3b, v150
	v_exp_f32_e32 v162, v162
	v_mul_f32_e32 v163, 0xbfb8aa3b, v151
	v_exp_f32_e32 v156, v156
	v_exp_f32_e32 v157, v157
	v_exp_f32_e32 v158, v158
	v_exp_f32_e32 v159, v159
	v_exp_f32_e32 v160, v160
	v_exp_f32_e32 v161, v161
	v_exp_f32_e32 v166, v163
	v_add_f32_e32 v162, 1.0, v162
	v_add_f32_e32 v156, 1.0, v156
	v_add_f32_e32 v157, 1.0, v157
	v_add_f32_e32 v158, 1.0, v158
	v_add_f32_e32 v159, 1.0, v159
	v_add_f32_e32 v160, 1.0, v160
	v_add_f32_e32 v161, 1.0, v161
	v_rcp_f32_e32 v163, v162
	v_add_f32_e32 v162, 1.0, v166
	v_rcp_f32_e32 v156, v156
	v_rcp_f32_e32 v157, v157
	v_rcp_f32_e32 v158, v158
	v_rcp_f32_e32 v159, v159
	v_rcp_f32_e32 v160, v160
	v_rcp_f32_e32 v161, v161
	v_rcp_f32_e32 v162, v162
	s_mov_b64 s[36:37], 0

.LBB0_2819:
	v_cvt_pk_bf16_f32 v140, v150, v152
	v_cvt_pk_bf16_f32 v141, v154, v157
	v_cvt_pk_bf16_f32 v142, v151, v153
	v_cvt_pk_bf16_f32 v143, v155, v156
	v_lshl_add_u64 v[234:235], v[148:149], 0, s[100:101]
	global_store_dwordx4 v[234:235], v[140:143], off
	s_cmp_gt_i32 s23, 1
	s_mov_b64 s[36:37], -1
	v_pk_fma_f32 v[140:141], v[68:69], v[136:137], v[72:73] op_sel:[0,1,0]
	v_pk_fma_f32 v[142:143], v[70:71], v[136:137], v[74:75] op_sel:[0,1,0]
	v_pk_fma_f32 v[132:133], v[132:133], v[136:137], v[140:141] op_sel_hi:[1,0,1]
	v_pk_fma_f32 v[134:135], v[134:135], v[136:137], v[142:143] op_sel_hi:[1,0,1]
	v_pk_fma_f32 v[140:141], v[60:61], v[136:137], v[64:65] op_sel:[0,1,0]
	v_pk_fma_f32 v[142:143], v[62:63], v[136:137], v[66:67] op_sel:[0,1,0]
	v_pk_fma_f32 v[128:129], v[128:129], v[136:137], v[140:141] op_sel_hi:[1,0,1]
	v_pk_fma_f32 v[130:131], v[130:131], v[136:137], v[142:143] op_sel_hi:[1,0,1]
	s_cbranch_scc0 .LBB0_2821
	v_mul_f32_e32 v146, 0xbfb8aa3b, v135
	v_mul_f32_e32 v140, 0xbfb8aa3b, v132
	v_mul_f32_e32 v141, 0xbfb8aa3b, v128
	v_mul_f32_e32 v142, 0xbfb8aa3b, v133
	v_mul_f32_e32 v143, 0xbfb8aa3b, v129
	v_mul_f32_e32 v144, 0xbfb8aa3b, v134
	v_mul_f32_e32 v145, 0xbfb8aa3b, v130
	v_exp_f32_e32 v146, v146
	v_mul_f32_e32 v147, 0xbfb8aa3b, v131
	v_exp_f32_e32 v140, v140
	v_exp_f32_e32 v141, v141
	v_exp_f32_e32 v142, v142
	v_exp_f32_e32 v143, v143
	v_exp_f32_e32 v144, v144
	v_exp_f32_e32 v145, v145
	v_exp_f32_e32 v148, v147
	v_add_f32_e32 v146, 1.0, v146
	v_add_f32_e32 v140, 1.0, v140
	v_add_f32_e32 v141, 1.0, v141
	v_add_f32_e32 v142, 1.0, v142
	v_add_f32_e32 v143, 1.0, v143
	v_add_f32_e32 v144, 1.0, v144
	v_add_f32_e32 v145, 1.0, v145
	v_rcp_f32_e32 v147, v146
	v_add_f32_e32 v146, 1.0, v148
	v_rcp_f32_e32 v140, v140
	v_rcp_f32_e32 v141, v141
	v_rcp_f32_e32 v142, v142
	v_rcp_f32_e32 v143, v143
	v_rcp_f32_e32 v144, v144
	v_rcp_f32_e32 v145, v145
	v_rcp_f32_e32 v146, v146
	s_mov_b64 s[36:37], 0

.LBB0_2831:
	v_cvt_pk_bf16_f32 v120, v130, v132
	v_cvt_pk_bf16_f32 v121, v134, v137
	v_cvt_pk_bf16_f32 v122, v131, v133
	v_cvt_pk_bf16_f32 v123, v135, v136
	v_lshl_add_u64 v[234:235], v[128:129], 0, s[100:101]
	global_store_dwordx4 v[234:235], v[120:123], off
	s_cmp_gt_i32 s23, 1
	s_mov_b64 s[36:37], -1
	v_pk_fma_f32 v[120:121], v[68:69], v[138:139], v[72:73] op_sel:[0,1,0]
	v_pk_fma_f32 v[122:123], v[70:71], v[138:139], v[74:75] op_sel:[0,1,0]
	v_pk_fma_f32 v[116:117], v[116:117], v[138:139], v[120:121] op_sel_hi:[1,0,1]
	v_pk_fma_f32 v[118:119], v[118:119], v[138:139], v[122:123] op_sel_hi:[1,0,1]
	v_pk_fma_f32 v[120:121], v[60:61], v[138:139], v[64:65] op_sel:[0,1,0]
	v_pk_fma_f32 v[122:123], v[62:63], v[138:139], v[66:67] op_sel:[0,1,0]
	v_pk_fma_f32 v[112:113], v[112:113], v[138:139], v[120:121] op_sel_hi:[1,0,1]
	v_pk_fma_f32 v[114:115], v[114:115], v[138:139], v[122:123] op_sel_hi:[1,0,1]
	s_cbranch_scc0 .LBB0_2833
	v_mul_f32_e32 v126, 0xbfb8aa3b, v119
	v_mul_f32_e32 v120, 0xbfb8aa3b, v116
	v_mul_f32_e32 v121, 0xbfb8aa3b, v112
	v_mul_f32_e32 v122, 0xbfb8aa3b, v117
	v_mul_f32_e32 v123, 0xbfb8aa3b, v113
	v_mul_f32_e32 v124, 0xbfb8aa3b, v118
	v_mul_f32_e32 v125, 0xbfb8aa3b, v114
	v_exp_f32_e32 v126, v126
	v_mul_f32_e32 v127, 0xbfb8aa3b, v115
	v_exp_f32_e32 v120, v120
	v_exp_f32_e32 v121, v121
	v_exp_f32_e32 v122, v122
	v_exp_f32_e32 v123, v123
	v_exp_f32_e32 v124, v124
	v_exp_f32_e32 v125, v125
	v_exp_f32_e32 v128, v127
	v_add_f32_e32 v126, 1.0, v126
	v_add_f32_e32 v120, 1.0, v120
	v_add_f32_e32 v121, 1.0, v121
	v_add_f32_e32 v122, 1.0, v122
	v_add_f32_e32 v123, 1.0, v123
	v_add_f32_e32 v124, 1.0, v124
	v_add_f32_e32 v125, 1.0, v125
	v_rcp_f32_e32 v127, v126
	v_add_f32_e32 v126, 1.0, v128
	v_rcp_f32_e32 v120, v120
	v_rcp_f32_e32 v121, v121
	v_rcp_f32_e32 v122, v122
	v_rcp_f32_e32 v123, v123
	v_rcp_f32_e32 v124, v124
	v_rcp_f32_e32 v125, v125
	v_rcp_f32_e32 v126, v126
	s_mov_b64 s[36:37], 0

.LBB0_2843:
	v_cvt_pk_bf16_f32 v104, v114, v116
	v_cvt_pk_bf16_f32 v105, v118, v121
	v_cvt_pk_bf16_f32 v106, v115, v117
	v_cvt_pk_bf16_f32 v107, v119, v120
	v_lshl_add_u64 v[234:235], v[112:113], 0, s[100:101]
	global_store_dwordx4 v[234:235], v[104:107], off
	s_cmp_gt_i32 s23, 1
	s_mov_b64 s[36:37], -1
	v_pk_fma_f32 v[104:105], v[68:69], v[100:101], v[72:73] op_sel:[0,1,0]
	v_pk_fma_f32 v[106:107], v[70:71], v[100:101], v[74:75] op_sel:[0,1,0]
	v_pk_fma_f32 v[96:97], v[96:97], v[100:101], v[104:105] op_sel_hi:[1,0,1]
	v_pk_fma_f32 v[98:99], v[98:99], v[100:101], v[106:107] op_sel_hi:[1,0,1]
	v_pk_fma_f32 v[104:105], v[60:61], v[100:101], v[64:65] op_sel:[0,1,0]
	v_pk_fma_f32 v[106:107], v[62:63], v[100:101], v[66:67] op_sel:[0,1,0]
	v_pk_fma_f32 v[92:93], v[92:93], v[100:101], v[104:105] op_sel_hi:[1,0,1]
	v_pk_fma_f32 v[94:95], v[94:95], v[100:101], v[106:107] op_sel_hi:[1,0,1]
	s_cbranch_scc0 .LBB0_2845
	v_mul_f32_e32 v110, 0xbfb8aa3b, v99
	v_mul_f32_e32 v104, 0xbfb8aa3b, v96
	v_mul_f32_e32 v105, 0xbfb8aa3b, v92
	v_mul_f32_e32 v106, 0xbfb8aa3b, v97
	v_mul_f32_e32 v107, 0xbfb8aa3b, v93
	v_mul_f32_e32 v108, 0xbfb8aa3b, v98
	v_mul_f32_e32 v109, 0xbfb8aa3b, v94
	v_exp_f32_e32 v110, v110
	v_mul_f32_e32 v111, 0xbfb8aa3b, v95
	v_exp_f32_e32 v104, v104
	v_exp_f32_e32 v105, v105
	v_exp_f32_e32 v106, v106
	v_exp_f32_e32 v107, v107
	v_exp_f32_e32 v108, v108
	v_exp_f32_e32 v109, v109
	v_exp_f32_e32 v112, v111
	v_add_f32_e32 v110, 1.0, v110
	v_add_f32_e32 v104, 1.0, v104
	v_add_f32_e32 v105, 1.0, v105
	v_add_f32_e32 v106, 1.0, v106
	v_add_f32_e32 v107, 1.0, v107
	v_add_f32_e32 v108, 1.0, v108
	v_add_f32_e32 v109, 1.0, v109
	v_rcp_f32_e32 v111, v110
	v_add_f32_e32 v110, 1.0, v112
	v_rcp_f32_e32 v104, v104
	v_rcp_f32_e32 v105, v105
	v_rcp_f32_e32 v106, v106
	v_rcp_f32_e32 v107, v107
	v_rcp_f32_e32 v108, v108
	v_rcp_f32_e32 v109, v109
	v_rcp_f32_e32 v110, v110
	s_mov_b64 s[36:37], 0

.LBB0_2855:
	v_cvt_pk_bf16_f32 v84, v94, v96
	v_cvt_pk_bf16_f32 v85, v98, v101
	v_cvt_pk_bf16_f32 v86, v95, v97
	v_cvt_pk_bf16_f32 v87, v99, v100
	v_lshl_add_u64 v[234:235], v[92:93], 0, s[100:101]
	global_store_dwordx4 v[234:235], v[84:87], off
	s_cmp_gt_i32 s23, 1
	s_mov_b64 s[36:37], -1
	v_pk_fma_f32 v[84:85], v[68:69], v[102:103], v[72:73] op_sel:[0,1,0]
	v_pk_fma_f32 v[86:87], v[70:71], v[102:103], v[74:75] op_sel:[0,1,0]
	v_pk_fma_f32 v[80:81], v[80:81], v[102:103], v[84:85] op_sel_hi:[1,0,1]
	v_pk_fma_f32 v[82:83], v[82:83], v[102:103], v[86:87] op_sel_hi:[1,0,1]
	v_pk_fma_f32 v[84:85], v[60:61], v[102:103], v[64:65] op_sel:[0,1,0]
	v_pk_fma_f32 v[86:87], v[62:63], v[102:103], v[66:67] op_sel:[0,1,0]
	v_pk_fma_f32 v[76:77], v[76:77], v[102:103], v[84:85] op_sel_hi:[1,0,1]
	v_pk_fma_f32 v[78:79], v[78:79], v[102:103], v[86:87] op_sel_hi:[1,0,1]
	s_cbranch_scc0 .LBB0_2857
	v_mul_f32_e32 v90, 0xbfb8aa3b, v83
	v_mul_f32_e32 v84, 0xbfb8aa3b, v80
	v_mul_f32_e32 v85, 0xbfb8aa3b, v76
	v_mul_f32_e32 v86, 0xbfb8aa3b, v81
	v_mul_f32_e32 v87, 0xbfb8aa3b, v77
	v_mul_f32_e32 v88, 0xbfb8aa3b, v82
	v_mul_f32_e32 v89, 0xbfb8aa3b, v78
	v_exp_f32_e32 v90, v90
	v_mul_f32_e32 v91, 0xbfb8aa3b, v79
	v_exp_f32_e32 v84, v84
	v_exp_f32_e32 v85, v85
	v_exp_f32_e32 v86, v86
	v_exp_f32_e32 v87, v87
	v_exp_f32_e32 v88, v88
	v_exp_f32_e32 v89, v89
	v_exp_f32_e32 v92, v91
	v_add_f32_e32 v90, 1.0, v90
	v_add_f32_e32 v84, 1.0, v84
	v_add_f32_e32 v85, 1.0, v85
	v_add_f32_e32 v86, 1.0, v86
	v_add_f32_e32 v87, 1.0, v87
	v_add_f32_e32 v88, 1.0, v88
	v_add_f32_e32 v89, 1.0, v89
	v_rcp_f32_e32 v91, v90
	v_add_f32_e32 v90, 1.0, v92
	v_rcp_f32_e32 v84, v84
	v_rcp_f32_e32 v85, v85
	v_rcp_f32_e32 v86, v86
	v_rcp_f32_e32 v87, v87
	v_rcp_f32_e32 v88, v88
	v_rcp_f32_e32 v89, v89
	v_rcp_f32_e32 v90, v90
	s_mov_b64 s[36:37], 0

.LBB0_2867:
	v_cvt_pk_bf16_f32 v36, v78, v80
	v_cvt_pk_bf16_f32 v37, v82, v85
	v_cvt_pk_bf16_f32 v38, v79, v81
	v_cvt_pk_bf16_f32 v39, v83, v84
	v_lshl_add_u64 v[234:235], v[76:77], 0, s[100:101]
	global_store_dwordx4 v[234:235], v[36:39], off
	s_cmp_gt_i32 s23, 1
	s_mov_b64 s[36:37], -1
	v_pk_fma_f32 v[36:37], v[68:69], v[48:49], v[72:73] op_sel:[0,1,0]
	v_pk_fma_f32 v[38:39], v[70:71], v[48:49], v[74:75] op_sel:[0,1,0]
	v_pk_fma_f32 v[28:29], v[28:29], v[48:49], v[36:37] op_sel_hi:[1,0,1]
	v_pk_fma_f32 v[30:31], v[30:31], v[48:49], v[38:39] op_sel_hi:[1,0,1]
	v_pk_fma_f32 v[36:37], v[60:61], v[48:49], v[64:65] op_sel:[0,1,0]
	v_pk_fma_f32 v[38:39], v[62:63], v[48:49], v[66:67] op_sel:[0,1,0]
	v_pk_fma_f32 v[24:25], v[24:25], v[48:49], v[36:37] op_sel_hi:[1,0,1]
	v_pk_fma_f32 v[26:27], v[26:27], v[48:49], v[38:39] op_sel_hi:[1,0,1]
	s_cbranch_scc0 .LBB0_2869
	v_mul_f32_e32 v54, 0xbfb8aa3b, v31
	v_mul_f32_e32 v36, 0xbfb8aa3b, v28
	v_mul_f32_e32 v37, 0xbfb8aa3b, v24
	v_mul_f32_e32 v38, 0xbfb8aa3b, v29
	v_mul_f32_e32 v39, 0xbfb8aa3b, v25
	v_mul_f32_e32 v52, 0xbfb8aa3b, v30
	v_mul_f32_e32 v53, 0xbfb8aa3b, v26
	v_exp_f32_e32 v54, v54
	v_mul_f32_e32 v55, 0xbfb8aa3b, v27
	v_exp_f32_e32 v36, v36
	v_exp_f32_e32 v37, v37
	v_exp_f32_e32 v38, v38
	v_exp_f32_e32 v39, v39
	v_exp_f32_e32 v52, v52
	v_exp_f32_e32 v53, v53
	v_exp_f32_e32 v76, v55
	v_add_f32_e32 v54, 1.0, v54
	v_add_f32_e32 v36, 1.0, v36
	v_add_f32_e32 v37, 1.0, v37
	v_add_f32_e32 v38, 1.0, v38
	v_add_f32_e32 v39, 1.0, v39
	v_add_f32_e32 v52, 1.0, v52
	v_add_f32_e32 v53, 1.0, v53
	v_rcp_f32_e32 v55, v54
	v_add_f32_e32 v54, 1.0, v76
	v_rcp_f32_e32 v36, v36
	v_rcp_f32_e32 v37, v37
	v_rcp_f32_e32 v38, v38
	v_rcp_f32_e32 v39, v39
	v_rcp_f32_e32 v52, v52
	v_rcp_f32_e32 v53, v53
	v_rcp_f32_e32 v54, v54
	s_mov_b64 s[36:37], 0

.LBB0_2879:
	v_cvt_pk_bf16_f32 v16, v26, v28
	v_cvt_pk_bf16_f32 v17, v30, v37
	v_cvt_pk_bf16_f32 v18, v27, v29
	v_cvt_pk_bf16_f32 v19, v31, v36
	v_lshl_add_u64 v[234:235], v[24:25], 0, s[100:101]
	global_store_dwordx4 v[234:235], v[16:19], off
	s_cmp_gt_i32 s23, 1
	s_mov_b64 s[36:37], -1
	v_pk_fma_f32 v[16:17], v[68:69], v[50:51], v[72:73] op_sel:[0,1,0]
	v_pk_fma_f32 v[18:19], v[70:71], v[50:51], v[74:75] op_sel:[0,1,0]
	v_pk_fma_f32 v[12:13], v[12:13], v[50:51], v[16:17] op_sel_hi:[1,0,1]
	v_pk_fma_f32 v[14:15], v[14:15], v[50:51], v[18:19] op_sel_hi:[1,0,1]
	v_pk_fma_f32 v[16:17], v[60:61], v[50:51], v[64:65] op_sel:[0,1,0]
	v_pk_fma_f32 v[18:19], v[62:63], v[50:51], v[66:67] op_sel:[0,1,0]
	v_pk_fma_f32 v[8:9], v[8:9], v[50:51], v[16:17] op_sel_hi:[1,0,1]
	v_pk_fma_f32 v[10:11], v[10:11], v[50:51], v[18:19] op_sel_hi:[1,0,1]
	s_cbranch_scc0 .LBB0_2881
	v_mul_f32_e32 v22, 0xbfb8aa3b, v15
	v_mul_f32_e32 v16, 0xbfb8aa3b, v12
	v_mul_f32_e32 v17, 0xbfb8aa3b, v8
	v_mul_f32_e32 v18, 0xbfb8aa3b, v13
	v_mul_f32_e32 v19, 0xbfb8aa3b, v9
	v_mul_f32_e32 v20, 0xbfb8aa3b, v14
	v_mul_f32_e32 v21, 0xbfb8aa3b, v10
	v_exp_f32_e32 v22, v22
	v_mul_f32_e32 v23, 0xbfb8aa3b, v11
	v_exp_f32_e32 v16, v16
	v_exp_f32_e32 v17, v17
	v_exp_f32_e32 v18, v18
	v_exp_f32_e32 v19, v19
	v_exp_f32_e32 v20, v20
	v_exp_f32_e32 v21, v21
	v_exp_f32_e32 v24, v23
	v_add_f32_e32 v22, 1.0, v22
	v_add_f32_e32 v16, 1.0, v16
	v_add_f32_e32 v17, 1.0, v17
	v_add_f32_e32 v18, 1.0, v18
	v_add_f32_e32 v19, 1.0, v19
	v_add_f32_e32 v20, 1.0, v20
	v_add_f32_e32 v21, 1.0, v21
	v_rcp_f32_e32 v23, v22
	v_add_f32_e32 v22, 1.0, v24
	v_rcp_f32_e32 v16, v16
	v_rcp_f32_e32 v17, v17
	v_rcp_f32_e32 v18, v18
	v_rcp_f32_e32 v19, v19
	v_rcp_f32_e32 v20, v20
	v_rcp_f32_e32 v21, v21
	v_rcp_f32_e32 v22, v22
	s_mov_b64 s[36:37], 0

.LBB0_2952:
	v_readlane_b32 s16, v255, 16
	v_bfe_u32 v7, v6, 5, 1
	v_readlane_b32 s17, v255, 17
	v_and_b32_e32 v139, 31, v6
	s_and_b64 vcc, exec, s[16:17]
	v_lshlrev_b32_e32 v132, 4, v7
	v_lshlrev_b32_e32 v8, 4, v6
	v_ashrrev_i32_e32 v176, 3, v6
	s_cbranch_vccnz .LBB0_2966
	s_ashr_i32 s5, s4, 31
	s_lshl_b64 s[16:17], s[4:5], 14
	s_or_b32 s16, s16, s53
	v_add_u32_e32 v2, s9, v139
	v_mov_b64_e32 v[0:1], s[16:17]
	v_mad_i64_i32 v[0:1], s[22:23], v2, s1, v[0:1]
	s_movk_i32 s5, 0x80
	v_mov_b64_e32 v[2:3], s[42:43]
	v_mad_u64_u32 v[2:3], s[22:23], v0, s5, v[2:3]
	v_mov_b32_e32 v0, v3
	v_mad_u64_u32 v[0:1], s[22:23], v1, s5, v[0:1]
	v_mov_b32_e32 v3, v0
	s_ashr_i32 s11, s10, 31
	v_mov_b32_e32 v64, 0
	s_lshl_b64 s[100:101], s[10:11], 15
	v_lshl_add_u64 v[0:1], s[100:101], 1, v[2:3]
	v_mov_b32_e32 v133, v64
	v_lshl_add_u64 v[0:1], v[0:1], 0, v[132:133]
	global_load_dwordx4 v[48:51], v[0:1], off
	global_load_dwordx4 v[52:55], v[0:1], off offset:32
	global_load_dwordx4 v[56:59], v[0:1], off offset:64
	global_load_dwordx4 v[60:63], v[0:1], off offset:96
	v_and_b32_e32 v0, 0x70, v8
	v_mov_b32_e32 v1, v64
	v_lshl_add_u64 v[4:5], s[42:43], 0, v[0:1]
	v_add_u32_e32 v0, s81, v176
	v_add_u32_e32 v0, 0xffffff80, v0
	v_mov_b32_e32 v76, 0
	v_mov_b32_e32 v77, v64
	v_cmp_gt_i32_e32 vcc, s52, v176
	v_cmp_lt_i32_e64 s[10:11], -1, v0
	v_mov_b32_e32 v78, v64
	v_mov_b32_e32 v79, v64
	v_mov_b64_e32 v[72:73], v[76:77]
	s_and_b64 s[22:23], vcc, s[10:11]
	s_mov_b32 s7, 0
	v_mov_b64_e32 v[74:75], v[78:79]
	v_mov_b32_e32 v68, 0
	v_mov_b32_e32 v69, 0
	v_mov_b32_e32 v70, 0
	v_mov_b32_e32 v71, 0
	s_and_saveexec_b64 s[10:11], s[22:23]
	s_cbranch_execz .LBB0_2955
	v_mov_b64_e32 v[2:3], s[16:17]
	v_mad_u64_u32 v[0:1], s[22:23], v0, s1, v[2:3]
	v_mad_u64_u32 v[2:3], s[22:23], v0, s5, v[4:5]
	v_mov_b32_e32 v0, v3
	v_mad_u64_u32 v[0:1], s[22:23], v1, s5, v[0:1]
	v_mov_b32_e32 v3, v0
	s_lshl_b64 s[100:101], s[6:7], 15
	v_lshl_add_u64 v[0:1], s[100:101], 1, v[2:3]
	s_mov_b32 s13, s7
	s_lshl_b64 s[100:101], s[12:13], 15
	v_lshl_add_u64 v[2:3], s[100:101], 1, v[2:3]
	global_load_dwordx4 v[68:71], v[0:1], off
	global_load_dwordx4 v[72:75], v[2:3], off
.LBB0_2955:
	s_or_b64 exec, exec, s[10:11]
	v_add_u32_e32 v0, 0x200, v6
	v_ashrrev_i32_e32 v1, 3, v0
	v_add_u32_e32 v0, s81, v1
	v_add_u32_e32 v0, 0xffffff80, v0
	v_cmp_gt_i32_e32 vcc, s52, v1
	v_cmp_lt_i32_e64 s[10:11], -1, v0
	s_and_b64 s[22:23], vcc, s[10:11]
	v_mov_b32_e32 v65, 0
	v_mov_b32_e32 v66, 0
	v_mov_b32_e32 v67, 0
	s_and_saveexec_b64 s[10:11], s[22:23]
	s_cbranch_execz .LBB0_2957
	v_mov_b64_e32 v[2:3], s[16:17]
	v_mad_u64_u32 v[0:1], s[22:23], v0, s1, v[2:3]
	v_mad_u64_u32 v[2:3], s[22:23], v0, s5, v[4:5]
	v_mov_b32_e32 v0, v3
	v_mad_u64_u32 v[0:1], s[22:23], v1, s5, v[0:1]
	v_mov_b32_e32 v3, v0
	s_lshl_b64 s[100:101], s[6:7], 15
	v_lshl_add_u64 v[0:1], s[100:101], 1, v[2:3]
	s_mov_b32 s13, s7
	s_lshl_b64 s[100:101], s[12:13], 15
	v_lshl_add_u64 v[2:3], s[100:101], 1, v[2:3]
	global_load_dwordx4 v[64:67], v[0:1], off
	global_load_dwordx4 v[76:79], v[2:3], off
.LBB0_2957:
	s_or_b64 exec, exec, s[10:11]
	v_add_u32_e32 v0, 0x400, v6
	v_ashrrev_i32_e32 v1, 3, v0
	v_add_u32_e32 v0, s81, v1
	v_mov_b32_e32 v96, 0
	v_add_u32_e32 v0, 0xffffff80, v0
	v_mov_b32_e32 v97, v96
	v_cmp_gt_i32_e32 vcc, s52, v1
	v_cmp_lt_i32_e64 s[10:11], -1, v0
	v_mov_b32_e32 v98, v96
	v_mov_b32_e32 v99, v96
	v_mov_b64_e32 v[84:85], v[96:97]
	s_and_b64 s[22:23], vcc, s[10:11]
	v_mov_b64_e32 v[86:87], v[98:99]
	v_mov_b32_e32 v80, v96
	v_mov_b32_e32 v81, v96
	v_mov_b32_e32 v82, v96
	v_mov_b32_e32 v83, v96
	s_and_saveexec_b64 s[10:11], s[22:23]
	s_cbranch_execz .LBB0_2959
	v_mov_b64_e32 v[2:3], s[16:17]
	v_mad_u64_u32 v[0:1], s[22:23], v0, s1, v[2:3]
	v_mad_u64_u32 v[2:3], s[22:23], v0, s5, v[4:5]
	v_mov_b32_e32 v0, v3
	v_mad_u64_u32 v[0:1], s[22:23], v1, s5, v[0:1]
	v_mov_b32_e32 v3, v0
	s_lshl_b64 s[100:101], s[6:7], 15
	v_lshl_add_u64 v[0:1], s[100:101], 1, v[2:3]
	s_mov_b32 s13, s7
	s_lshl_b64 s[100:101], s[12:13], 15
	v_lshl_add_u64 v[2:3], s[100:101], 1, v[2:3]
	global_load_dwordx4 v[80:83], v[0:1], off
	global_load_dwordx4 v[84:87], v[2:3], off
.LBB0_2959:
	s_or_b64 exec, exec, s[10:11]
	v_add_u32_e32 v0, 0x600, v6
	v_ashrrev_i32_e32 v1, 3, v0
	v_add_u32_e32 v0, s81, v1
	v_add_u32_e32 v0, 0xffffff80, v0
	v_cmp_gt_i32_e32 vcc, s52, v1
	v_cmp_lt_i32_e64 s[10:11], -1, v0
	s_and_b64 s[22:23], vcc, s[10:11]
	v_mov_b32_e32 v92, v96
	v_mov_b32_e32 v93, v96
	v_mov_b32_e32 v94, v96
	v_mov_b32_e32 v95, v96
	s_and_saveexec_b64 s[10:11], s[22:23]
	s_cbranch_execz .LBB0_2961
	v_mov_b64_e32 v[2:3], s[16:17]
	v_mad_u64_u32 v[0:1], s[22:23], v0, s1, v[2:3]
	v_mad_u64_u32 v[2:3], s[22:23], v0, s5, v[4:5]
	v_mov_b32_e32 v0, v3
	v_mad_u64_u32 v[0:1], s[22:23], v1, s5, v[0:1]
	v_mov_b32_e32 v3, v0
	s_lshl_b64 s[100:101], s[6:7], 15
	v_lshl_add_u64 v[0:1], s[100:101], 1, v[2:3]
	s_mov_b32 s13, s7
	s_lshl_b64 s[100:101], s[12:13], 15
	v_lshl_add_u64 v[2:3], s[100:101], 1, v[2:3]
	global_load_dwordx4 v[92:95], v[0:1], off
	global_load_dwordx4 v[96:99], v[2:3], off
.LBB0_2961:
	s_or_b64 exec, exec, s[10:11]
	v_add_u32_e32 v0, 0x800, v6
	v_ashrrev_i32_e32 v0, 3, v0
	v_add_u32_e32 v1, s81, v0
	v_cmp_gt_i32_e32 vcc, s52, v0
	v_mov_b32_e32 v0, 0
	v_add_u32_e32 v9, 0xffffff80, v1
	v_mov_b32_e32 v2, v0
	v_mov_b32_e32 v3, v0
	v_cmp_lt_i32_e64 s[10:11], -1, v9
	v_mov_b32_e32 v1, v0
	v_mov_b64_e32 v[106:107], v[2:3]
	s_and_b64 s[22:23], vcc, s[10:11]
	v_mov_b64_e32 v[104:105], v[0:1]
	v_mov_b32_e32 v100, 0
	v_mov_b32_e32 v101, 0
	v_mov_b32_e32 v102, 0
	v_mov_b32_e32 v103, 0
	s_and_saveexec_b64 s[10:11], s[22:23]
	s_cbranch_execz .LBB0_2963
	v_mov_b64_e32 v[2:3], s[16:17]
	v_mad_u64_u32 v[2:3], s[22:23], v9, s1, v[2:3]
	v_mad_u64_u32 v[10:11], s[22:23], v2, s5, v[4:5]
	v_mov_b32_e32 v2, v11
	v_mad_u64_u32 v[2:3], s[22:23], v3, s5, v[2:3]
	v_mov_b32_e32 v11, v2
	s_lshl_b64 s[100:101], s[6:7], 15
	v_lshl_add_u64 v[2:3], s[100:101], 1, v[10:11]
	s_mov_b32 s13, s7
	s_lshl_b64 s[100:101], s[12:13], 15
	v_lshl_add_u64 v[10:11], s[100:101], 1, v[10:11]
	global_load_dwordx4 v[100:103], v[2:3], off
	global_load_dwordx4 v[104:107], v[10:11], off
.LBB0_2963:
	s_or_b64 exec, exec, s[10:11]
	v_add_u32_e32 v1, 0xa00, v6
	v_ashrrev_i32_e32 v2, 3, v1
	v_add_u32_e32 v1, s81, v2
	v_add_u32_e32 v1, 0xffffff80, v1
	v_cmp_gt_i32_e32 vcc, s52, v2
	v_cmp_lt_i32_e64 s[10:11], -1, v1
	s_and_b64 s[22:23], vcc, s[10:11]
	v_mov_b32_e32 v110, 0
	v_mov_b32_e32 v109, 0
	v_mov_b32_e32 v108, 0
	v_mov_b32_e32 v115, 0
	v_mov_b32_e32 v114, 0
	v_mov_b32_e32 v113, 0
	v_mov_b32_e32 v112, 0
	s_and_saveexec_b64 s[10:11], s[22:23]
	s_cbranch_execz .LBB0_2965
	v_mov_b64_e32 v[2:3], s[16:17]
	v_mad_u64_u32 v[0:1], s[16:17], v1, s1, v[2:3]
	v_mad_u64_u32 v[2:3], s[16:17], v0, s5, v[4:5]
	v_mov_b32_e32 v0, v3
	v_mad_u64_u32 v[0:1], s[16:17], v1, s5, v[0:1]
	v_mov_b32_e32 v3, v0
	s_lshl_b64 s[100:101], s[6:7], 15
	v_lshl_add_u64 v[0:1], s[100:101], 1, v[2:3]
	s_mov_b32 s13, s7
	s_lshl_b64 s[100:101], s[12:13], 15
	v_lshl_add_u64 v[2:3], s[100:101], 1, v[2:3]
	global_load_dwordx4 v[108:111], v[0:1], off
	global_load_dwordx4 v[112:115], v[2:3], off
	s_waitcnt vmcnt(1)
	v_mov_b32_e32 v0, v111

.LBB0_2967:
	v_readlane_b32 s6, v255, 16
	v_readlane_b32 s7, v255, 17
	v_and_b32_e32 v0, 63, v6
	s_and_b64 vcc, exec, s[6:7]
	s_cbranch_vccnz .LBB0_3013
	v_mov_b32_e32 v88, 0
	v_and_b32_e32 v2, 0x70, v8
	v_mov_b32_e32 v3, v88
	v_add_u32_e32 v1, 0, v2
	v_lshl_add_u64 v[136:137], s[42:43], 0, v[2:3]
	v_add_u32_e32 v2, 0x200, v6
	v_ashrrev_i32_e32 v177, 3, v2
	v_add_u32_e32 v2, 0x400, v6
	v_ashrrev_i32_e32 v179, 3, v2
	v_add_u32_e32 v2, 0x600, v6
	v_ashrrev_i32_e32 v181, 3, v2
	v_add_u32_e32 v2, 0x800, v6
	v_ashrrev_i32_e32 v183, 3, v2
	v_add_u32_e32 v2, 0xa00, v6
	v_cmp_gt_u32_e64 s[6:7], 32, v0
	v_and_b32_e32 v0, 3, v6
	v_ashrrev_i32_e32 v185, 3, v2
	v_lshlrev_b32_e32 v4, 1, v6
	v_lshrrev_b32_e32 v2, 1, v6
	s_movk_i32 s65, 0x90
	v_lshlrev_b32_e32 v0, 3, v0
	s_ashr_i32 s60, s19, 7
	s_lshl_b32 s61, s18, 5
	v_lshlrev_b32_e32 v134, 3, v7
	v_and_b32_e32 v3, 19, v6
	v_and_b32_e32 v5, 8, v4
	v_and_b32_e32 v8, 4, v2
	v_lshrrev_b32_e32 v9, 2, v6
	v_lshlrev_b32_e32 v2, 2, v7
	v_mul_lo_u32 v7, v176, s65
	v_mul_lo_u32 v10, v177, s65
	v_mul_lo_u32 v11, v179, s65
	v_mul_lo_u32 v12, v181, s65
	v_mul_lo_u32 v13, v183, s65
	v_mul_lo_u32 v14, v185, s65
	v_and_or_b32 v138, v4, 32, v0
	s_mov_b32 s18, 0x41a00000
	s_mov_b32 s22, 2.0
	s_mov_b32 s24, 4.0
	s_mov_b32 s26, 0x40c00000
	s_mov_b32 s34, 0x41800000
	s_mov_b32 s36, 0x41900000
	s_mov_b32 s48, 0x41b00000
	v_mbcnt_lo_u32_b32 v0, -1, 0
	s_mov_b32 s17, 0
	s_and_b32 s64, s61, 32
	v_add_u32_e32 v133, 0xffffff80, v176
	v_add_u32_e32 v178, 0xffffff80, v177
	v_add_u32_e32 v180, 0xffffff80, v179
	v_add_u32_e32 v182, 0xffffff80, v181
	v_add_u32_e32 v184, 0xffffff80, v183
	v_add_u32_e32 v186, 0xffffff80, v185
	v_cndmask_b32_e64 v187, 0, 1.0, s[6:7]
	v_sub_u32_e32 v188, v139, v134
	v_and_or_b32 v189, v9, 3, v134
	v_or3_b32 v190, v3, v5, v8
	v_add_u32_e32 v191, v1, v7
	v_add_u32_e32 v192, v1, v10
	v_add_u32_e32 v193, v1, v11
	v_add_u32_e32 v194, v1, v12
	v_add_u32_e32 v195, v1, v13
	v_add_u32_e32 v196, v1, v14
	s_movk_i32 s66, 0x80
	s_mov_b32 s19, 0x41a80000
	s_mov_b32 s23, 0x40400000
	s_mov_b32 s25, 0x40a00000
	s_mov_b32 s27, 0x40e00000
	s_mov_b32 s35, 0x41880000
	s_mov_b32 s37, 0x41980000
	s_mov_b32 s49, 0x41b80000
	s_mov_b32 s67, 0xff800000
	v_lshlrev_b32_e32 v140, 1, v2
	v_mov_b32_e32 v197, 0x3fb8aa3b
	v_mov_b32_e32 v198, 0x42800000
	v_mbcnt_hi_u32_b32 v199, -1, v0
	v_mov_b32_e32 v200, 0xff800000
	s_mov_b32 s68, s2
	s_waitcnt vmcnt(0)
	s_branch .LBB0_2970

.LBB0_2988:
	s_ashr_i32 s51, s50, 31
	s_lshl_b64 s[46:47], s[50:51], 14
	s_or_b32 s46, s46, s73
	v_add_u32_e32 v2, s70, v139
	v_mov_b64_e32 v[0:1], s[46:47]
	v_mad_i64_i32 v[0:1], s[84:85], v2, s72, v[0:1]
	v_mov_b64_e32 v[2:3], s[42:43]
	v_mad_u64_u32 v[2:3], s[84:85], v0, s66, v[2:3]
	v_mov_b32_e32 v0, v3
	v_mad_u64_u32 v[0:1], s[84:85], v1, s66, v[0:1]
	v_mov_b32_e32 v3, v0
	s_ashr_i32 s11, s10, 31
	s_lshl_b64 s[100:101], s[10:11], 15
	v_lshl_add_u64 v[0:1], s[100:101], 1, v[2:3]
	v_lshlrev_b32_e32 v2, 1, v134
	v_mov_b32_e32 v3, v88
	v_lshl_add_u64 v[0:1], v[0:1], 0, v[2:3]
	global_load_dwordx4 v[116:119], v[0:1], off
	global_load_dwordx4 v[120:123], v[0:1], off offset:32
	global_load_dwordx4 v[124:127], v[0:1], off offset:64
	global_load_dwordx4 v[128:131], v[0:1], off offset:96
	v_add_u32_e32 v0, s69, v133
	v_mov_b32_e32 v89, v88
	v_cmp_gt_i32_e32 vcc, s52, v176
	v_cmp_lt_i32_e64 s[10:11], -1, v0
	v_mov_b32_e32 v90, v88
	v_mov_b32_e32 v91, v88
	v_mov_b64_e32 v[72:73], v[88:89]
	s_and_b64 s[84:85], vcc, s[10:11]
	v_mov_b32_e32 v64, 0
	v_mov_b64_e32 v[74:75], v[90:91]
	v_mov_b32_e32 v68, 0
	v_mov_b32_e32 v69, 0
	v_mov_b32_e32 v70, 0
	v_mov_b32_e32 v71, 0
	s_and_saveexec_b64 s[10:11], s[84:85]
	s_cbranch_execz .LBB0_2990
	v_mov_b64_e32 v[2:3], s[46:47]
	v_mad_u64_u32 v[0:1], s[84:85], v0, s72, v[2:3]
	v_mad_u64_u32 v[2:3], s[84:85], v0, s66, v[136:137]
	v_mov_b32_e32 v0, v3
	v_mad_u64_u32 v[0:1], s[84:85], v1, s66, v[0:1]
	v_mov_b32_e32 v3, v0
	s_lshl_b64 s[100:101], s[16:17], 15
	v_lshl_add_u64 v[0:1], s[100:101], 1, v[2:3]
	s_mov_b32 s13, s17
	s_lshl_b64 s[100:101], s[12:13], 15
	v_lshl_add_u64 v[2:3], s[100:101], 1, v[2:3]
	global_load_dwordx4 v[68:71], v[0:1], off
	global_load_dwordx4 v[72:75], v[2:3], off
.LBB0_2990:
	s_or_b64 exec, exec, s[10:11]
	v_add_u32_e32 v0, s69, v178
	v_cmp_gt_i32_e32 vcc, s52, v177
	v_cmp_lt_i32_e64 s[10:11], -1, v0
	v_mov_b64_e32 v[76:77], v[88:89]
	s_and_b64 s[84:85], vcc, s[10:11]
	v_mov_b64_e32 v[78:79], v[90:91]
	v_mov_b32_e32 v65, 0
	v_mov_b32_e32 v66, 0
	v_mov_b32_e32 v67, 0
	s_and_saveexec_b64 s[10:11], s[84:85]
	s_cbranch_execz .LBB0_2992
	v_mov_b64_e32 v[2:3], s[46:47]
	v_mad_u64_u32 v[0:1], s[84:85], v0, s72, v[2:3]
	v_mad_u64_u32 v[2:3], s[84:85], v0, s66, v[136:137]
	v_mov_b32_e32 v0, v3
	v_mad_u64_u32 v[0:1], s[84:85], v1, s66, v[0:1]
	v_mov_b32_e32 v3, v0
	s_lshl_b64 s[100:101], s[16:17], 15
	v_lshl_add_u64 v[0:1], s[100:101], 1, v[2:3]
	s_mov_b32 s13, s17
	s_lshl_b64 s[100:101], s[12:13], 15
	v_lshl_add_u64 v[2:3], s[100:101], 1, v[2:3]
	global_load_dwordx4 v[64:67], v[0:1], off
	global_load_dwordx4 v[76:79], v[2:3], off
.LBB0_2992:
	s_or_b64 exec, exec, s[10:11]
	v_add_u32_e32 v0, s69, v180
	v_mov_b32_e32 v89, v88
	v_cmp_gt_i32_e32 vcc, s52, v179
	v_cmp_lt_i32_e64 s[10:11], -1, v0
	v_mov_b32_e32 v90, v88
	v_mov_b32_e32 v91, v88
	v_mov_b64_e32 v[84:85], v[88:89]
	s_and_b64 s[84:85], vcc, s[10:11]
	v_mov_b32_e32 v92, 0
	v_mov_b64_e32 v[86:87], v[90:91]
	v_mov_b32_e32 v80, 0
	v_mov_b32_e32 v81, 0
	v_mov_b32_e32 v82, 0
	v_mov_b32_e32 v83, 0
	s_and_saveexec_b64 s[10:11], s[84:85]
	s_cbranch_execz .LBB0_2994
	v_mov_b64_e32 v[2:3], s[46:47]
	v_mad_u64_u32 v[0:1], s[84:85], v0, s72, v[2:3]
	v_mad_u64_u32 v[2:3], s[84:85], v0, s66, v[136:137]
	v_mov_b32_e32 v0, v3
	v_mad_u64_u32 v[0:1], s[84:85], v1, s66, v[0:1]
	v_mov_b32_e32 v3, v0
	s_lshl_b64 s[100:101], s[16:17], 15
	v_lshl_add_u64 v[0:1], s[100:101], 1, v[2:3]
	s_mov_b32 s13, s17
	s_lshl_b64 s[100:101], s[12:13], 15
	v_lshl_add_u64 v[2:3], s[100:101], 1, v[2:3]
	global_load_dwordx4 v[80:83], v[0:1], off
	global_load_dwordx4 v[84:87], v[2:3], off
.LBB0_2994:
	s_or_b64 exec, exec, s[10:11]
	v_add_u32_e32 v0, s69, v182
	v_cmp_gt_i32_e32 vcc, s52, v181
	v_cmp_lt_i32_e64 s[10:11], -1, v0
	v_mov_b64_e32 v[98:99], v[90:91]
	s_and_b64 s[84:85], vcc, s[10:11]
	v_mov_b64_e32 v[96:97], v[88:89]
	v_mov_b32_e32 v93, 0
	v_mov_b32_e32 v94, 0
	v_mov_b32_e32 v95, 0
	s_and_saveexec_b64 s[10:11], s[84:85]
	s_cbranch_execz .LBB0_2996
	v_mov_b64_e32 v[2:3], s[46:47]
	v_mad_u64_u32 v[0:1], s[84:85], v0, s72, v[2:3]
	v_mad_u64_u32 v[2:3], s[84:85], v0, s66, v[136:137]
	v_mov_b32_e32 v0, v3
	v_mad_u64_u32 v[0:1], s[84:85], v1, s66, v[0:1]
	v_mov_b32_e32 v3, v0
	s_lshl_b64 s[100:101], s[16:17], 15
	v_lshl_add_u64 v[0:1], s[100:101], 1, v[2:3]
	s_mov_b32 s13, s17
	s_lshl_b64 s[100:101], s[12:13], 15
	v_lshl_add_u64 v[2:3], s[100:101], 1, v[2:3]
	global_load_dwordx4 v[92:95], v[0:1], off
	global_load_dwordx4 v[96:99], v[2:3], off
.LBB0_2996:
	s_or_b64 exec, exec, s[10:11]
	v_add_u32_e32 v0, s69, v184
	v_mov_b32_e32 v90, v88
	v_mov_b32_e32 v91, v88
	v_cmp_gt_i32_e32 vcc, s52, v183
	v_cmp_lt_i32_e64 s[10:11], -1, v0
	v_mov_b32_e32 v89, v88
	v_mov_b64_e32 v[106:107], v[90:91]
	s_and_b64 s[84:85], vcc, s[10:11]
	v_mov_b32_e32 v111, 0
	v_mov_b64_e32 v[104:105], v[88:89]
	v_mov_b32_e32 v100, 0
	v_mov_b32_e32 v101, 0
	v_mov_b32_e32 v102, 0
	v_mov_b32_e32 v103, 0
	s_and_saveexec_b64 s[10:11], s[84:85]
	s_cbranch_execz .LBB0_2998
	v_mov_b64_e32 v[2:3], s[46:47]
	v_mad_u64_u32 v[0:1], s[84:85], v0, s72, v[2:3]
	v_mad_u64_u32 v[2:3], s[84:85], v0, s66, v[136:137]
	v_mov_b32_e32 v0, v3
	v_mad_u64_u32 v[0:1], s[84:85], v1, s66, v[0:1]
	v_mov_b32_e32 v3, v0
	s_lshl_b64 s[100:101], s[16:17], 15
	v_lshl_add_u64 v[0:1], s[100:101], 1, v[2:3]
	s_mov_b32 s13, s17
	s_lshl_b64 s[100:101], s[12:13], 15
	v_lshl_add_u64 v[2:3], s[100:101], 1, v[2:3]
	global_load_dwordx4 v[100:103], v[0:1], off
	global_load_dwordx4 v[104:107], v[2:3], off
.LBB0_2998:
	s_or_b64 exec, exec, s[10:11]
	v_add_u32_e32 v0, s69, v186
	v_cmp_gt_i32_e32 vcc, s52, v185
	v_cmp_lt_i32_e64 s[10:11], -1, v0
	s_and_b64 s[84:85], vcc, s[10:11]
	v_mov_b32_e32 v110, 0
	v_mov_b32_e32 v109, 0
	v_mov_b32_e32 v108, 0
	v_mov_b32_e32 v115, 0
	v_mov_b32_e32 v114, 0
	v_mov_b32_e32 v113, 0
	v_mov_b32_e32 v112, 0
	s_and_saveexec_b64 s[10:11], s[84:85]
	s_cbranch_execz .LBB0_3000
	v_mov_b64_e32 v[2:3], s[46:47]
	v_mad_u64_u32 v[0:1], s[46:47], v0, s72, v[2:3]
	v_mad_u64_u32 v[2:3], s[46:47], v0, s66, v[136:137]
	v_mov_b32_e32 v0, v3
	v_mad_u64_u32 v[0:1], s[46:47], v1, s66, v[0:1]
	v_mov_b32_e32 v3, v0
	s_lshl_b64 s[100:101], s[16:17], 15
	v_lshl_add_u64 v[0:1], s[100:101], 1, v[2:3]
	s_mov_b32 s13, s17
	s_lshl_b64 s[100:101], s[12:13], 15
	v_lshl_add_u64 v[2:3], s[100:101], 1, v[2:3]
	global_load_dwordx4 v[108:111], v[0:1], off
	global_load_dwordx4 v[112:115], v[2:3], off
